# residual-add GEMM epilogues (P2,P8,P11,P13): 32 serialized base-tile load/wait/store round trips replaced by loads batched 16 ahead in spare VGPRs with counted vmcnt
# speedup vs baseline: 1.0352x; 1.0201x over previous
; __device__ __forceinline__ unsigned pk2(float lo, float hi) { f32x2_t v = {lo, hi}; bf16x2_t b = __builtin_convertvector(v, bf16x2_t); return __builtin_bit_cast(unsigned, b); }
; __device__ __forceinline__ float xor16_sum(float v) { float a = v, b = v; swap16(a, b); return a + b; }
; __device__ __forceinline__ float xor32_sum(float v) { float a = v, b = v; swap32(a, b); return a + b; }
;     __device__ __forceinline__ void operator()(const f32x4 (&acc)[2][2][4][2], const Unit& u, int wr, int wc, int fr, int fq) const {
;         const int row0 = u.pm * BM + wr * 64 + fr; constexpr int ldc = 2048; constexpr float alpha = 0.5f * ALPHA2;
;         bf16_t* const xb = (bf16_t*)(ws + XBOFF); __attribute__((address_space(1))) float* const ss = (__attribute__((address_space(1))) float*)(ws + SSOFF);
; #pragma unroll
;         for (int ai = 0; ai < 2; ++ai)
; #pragma unroll
;             for (int m = 0; m < 4; ++m) {
;                 const int row = row0 + ai * HALF + m * 16; float sq = 0.f;
; #pragma unroll
;                 for (int bj = 0; bj < 2; ++bj)
; #pragma unroll
;                     for (int n = 0; n < 2; ++n) {
;                         const size_t idx = (size_t)row * ldc + u.pn * BM + bj * HALF + wc * 32 + 8 * fq + 4 * n;
;                         const f32x4 b = *(const f32x4*)(base + idx);
;                         const f32x4 v = b + acc[ai][bj][m][n] * alpha;
;                         *(f32x4*)(out + idx) = v;
;                         if (NORM) { u32x2 w; w.x = pk2(v[0], v[1]); w.y = pk2(v[2], v[3]); *(u32x2*)(xb + idx) = w; sq += (v[0] * v[0] + v[1] * v[1]) + (v[2] * v[2] + v[3] * v[3]); }
;                     }
;                 if (NORM) { sq = xor16_sum(sq); sq = xor32_sum(sq); if (fq == 0) __hip_atomic_fetch_add(ss + row, sq, __ATOMIC_RELAXED, __HIP_MEMORY_SCOPE_AGENT); }
.LBB0_423:
	v_lshl_add_u32 v148, s14, 8, v137
	s_lshl_b32 s12, s16, 8
	s_ashr_i32 s13, s12, 31
	v_ashrrev_i32_e32 v149, 31, v148
	v_mov_b32_e32 v147, s13
	v_or_b32_e32 v146, s12, v136
	v_lshlrev_b64 v[154:155], 11, v[148:149]
	v_lshl_add_u64 v[158:159], v[154:155], 0, v[146:147]
	v_lshlrev_b64 v[160:161], 2, v[158:159]
	v_lshl_add_u64 v[162:163], s[52:53], 0, v[160:161]
	v_mov_b32_e32 v232, v162
	v_mov_b32_e32 v233, v163
	v_mov_b32_e32 v231, 0
	v_mov_b32_e32 v230, 0x0
	v_lshl_add_u64 v[228:229], v[232:233], 0, v[230:231]
	global_load_dwordx4 v[164:167], v[228:229], off
	global_load_dwordx4 v[168:171], v[228:229], off offset:16
	global_load_dwordx4 v[172:175], v[228:229], off offset:512
	global_load_dwordx4 v[176:179], v[228:229], off offset:528
	v_mov_b32_e32 v230, 0x20000
	v_lshl_add_u64 v[228:229], v[232:233], 0, v[230:231]
	global_load_dwordx4 v[180:183], v[228:229], off
	global_load_dwordx4 v[188:191], v[228:229], off offset:16
	global_load_dwordx4 v[192:195], v[228:229], off offset:512
	global_load_dwordx4 v[196:199], v[228:229], off offset:528
	v_mov_b32_e32 v230, 0x40000
	v_lshl_add_u64 v[228:229], v[232:233], 0, v[230:231]
	global_load_dwordx4 v[200:203], v[228:229], off
	global_load_dwordx4 v[204:207], v[228:229], off offset:16
	global_load_dwordx4 v[208:211], v[228:229], off offset:512
	global_load_dwordx4 v[212:215], v[228:229], off offset:528
	v_mov_b32_e32 v230, 0x60000
	v_lshl_add_u64 v[228:229], v[232:233], 0, v[230:231]
	global_load_dwordx4 v[216:219], v[228:229], off
	global_load_dwordx4 v[220:223], v[228:229], off offset:16
	global_load_dwordx4 v[224:227], v[228:229], off offset:512
	global_load_dwordx4 v[234:237], v[228:229], off offset:528
	v_lshlrev_b64 v[158:159], 1, v[158:159]
	s_waitcnt vmcnt(12)
	v_pk_fma_f32 v[126:127], v[126:127], 0.5, v[166:167] op_sel_hi:[1,0,1]
	v_pk_fma_f32 v[124:125], v[124:125], 0.5, v[164:165] op_sel_hi:[1,0,1]
	v_lshl_add_u64 v[154:155], s[30:31], 0, v[160:161]
	global_store_dwordx4 v[154:155], v[124:127], off
	v_cvt_pk_bf16_f32 v156, v124, v125
	v_cvt_pk_bf16_f32 v157, v126, v127
	v_mul_f32_e32 v125, v125, v125
	v_lshl_add_u64 v[160:161], s[40:41], 0, v[158:159]
	v_fmac_f32_e32 v125, v124, v124
	v_mul_f32_e32 v124, v127, v127
	global_store_dwordx2 v[160:161], v[156:157], off
	v_fmac_f32_e32 v124, v126, v126
	v_add_f32_e32 v156, v125, v124
	v_pk_fma_f32 v[122:123], v[122:123], 0.5, v[170:171] op_sel_hi:[1,0,1]
	v_pk_fma_f32 v[120:121], v[120:121], 0.5, v[168:169] op_sel_hi:[1,0,1]
	global_store_dwordx4 v[154:155], v[120:123], off offset:16
	v_cvt_pk_bf16_f32 v124, v120, v121
	v_or_b32_e32 v126, 8, v158
	v_mul_f32_e32 v121, v121, v121
	v_mov_b32_e32 v127, v159
	v_fmac_f32_e32 v121, v120, v120
	v_mul_f32_e32 v120, v123, v123
	v_cvt_pk_bf16_f32 v125, v122, v123
	v_lshl_add_u64 v[126:127], s[40:41], 0, v[126:127]
	v_fmac_f32_e32 v120, v122, v122
	global_store_dwordx2 v[126:127], v[124:125], off
	v_add_f32_e32 v120, v121, v120
	v_add_f32_e32 v124, v156, v120
	v_pk_fma_f32 v[118:119], v[118:119], 0.5, v[174:175] op_sel_hi:[1,0,1]
	v_pk_fma_f32 v[116:117], v[116:117], 0.5, v[172:173] op_sel_hi:[1,0,1]
	global_store_dwordx4 v[154:155], v[116:119], off offset:512
	v_cvt_pk_bf16_f32 v120, v116, v117
	v_or_b32_e32 v122, 0x100, v158
	v_mul_f32_e32 v117, v117, v117
	v_mov_b32_e32 v123, v159
	v_fmac_f32_e32 v117, v116, v116
	v_mul_f32_e32 v116, v119, v119
	v_cvt_pk_bf16_f32 v121, v118, v119
	v_lshl_add_u64 v[122:123], s[40:41], 0, v[122:123]
	v_fmac_f32_e32 v116, v118, v118
	global_store_dwordx2 v[122:123], v[120:121], off
	v_add_f32_e32 v116, v117, v116
	v_add_f32_e32 v120, v124, v116
	v_or_b32_e32 v158, 0x108, v158
	v_pk_fma_f32 v[114:115], v[114:115], 0.5, v[178:179] op_sel_hi:[1,0,1]
	v_pk_fma_f32 v[112:113], v[112:113], 0.5, v[176:177] op_sel_hi:[1,0,1]
	v_mov_b32_e32 v230, 0x100000
	v_lshl_add_u64 v[228:229], v[232:233], 0, v[230:231]
	global_load_dwordx4 v[164:167], v[228:229], off
	global_load_dwordx4 v[168:171], v[228:229], off offset:16
	global_load_dwordx4 v[172:175], v[228:229], off offset:512
	global_load_dwordx4 v[176:179], v[228:229], off offset:528
	global_store_dwordx4 v[154:155], v[112:115], off offset:528
	v_cvt_pk_bf16_f32 v116, v112, v113
	v_cvt_pk_bf16_f32 v117, v114, v115
	v_mul_f32_e32 v113, v113, v113
	v_fmac_f32_e32 v113, v112, v112
	v_mul_f32_e32 v112, v115, v115
	v_fmac_f32_e32 v112, v114, v114
	v_add_f32_e32 v112, v113, v112
	v_add_f32_e32 v112, v120, v112
	v_mov_b32_e32 v113, v112
	s_nop 1
	v_permlane16_swap_b32 v112, v113
	v_lshl_add_u64 v[118:119], s[40:41], 0, v[158:159]
	v_add_f32_e32 v112, v112, v113
	v_mov_b32_e32 v113, v112
	global_store_dwordx2 v[118:119], v[116:117], off
	s_nop 1
	v_permlane32_swap_b32 v112, v113
	s_and_saveexec_b64 s[12:13], s[2:3]
	s_cbranch_execz .LBB0_425
	v_lshl_add_u64 v[114:115], v[148:149], 2, s[90:91]
	v_add_f32_e32 v112, v112, v113
	global_atomic_add_f32 v[114:115], v112, off
; __device__ __forceinline__ unsigned pk2(float lo, float hi) { f32x2_t v = {lo, hi}; bf16x2_t b = __builtin_convertvector(v, bf16x2_t); return __builtin_bit_cast(unsigned, b); }
; __device__ __forceinline__ float xor16_sum(float v) { float a = v, b = v; swap16(a, b); return a + b; }
; __device__ __forceinline__ float xor32_sum(float v) { float a = v, b = v; swap32(a, b); return a + b; }
;     __device__ __forceinline__ void operator()(const f32x4 (&acc)[2][2][4][2], const Unit& u, int wr, int wc, int fr, int fq) const {
;     ...
;                 const int row = row0 + ai * HALF + m * 16; float sq = 0.f;
; #pragma unroll
;                 for (int bj = 0; bj < 2; ++bj)
; #pragma unroll
;                     for (int n = 0; n < 2; ++n) {
;                         const size_t idx = (size_t)row * ldc + u.pn * BM + bj * HALF + wc * 32 + 8 * fq + 4 * n;
;                         const f32x4 b = *(const f32x4*)(base + idx);
;                         const f32x4 v = b + acc[ai][bj][m][n] * alpha;
;                         *(f32x4*)(out + idx) = v;
;                         if (NORM) { u32x2 w; w.x = pk2(v[0], v[1]); w.y = pk2(v[2], v[3]); *(u32x2*)(xb + idx) = w; sq += (v[0] * v[0] + v[1] * v[1]) + (v[2] * v[2] + v[3] * v[3]); }
;                     }
;                 if (NORM) { sq = xor16_sum(sq); sq = xor32_sum(sq); if (fq == 0) __hip_atomic_fetch_add(ss + row, sq, __ATOMIC_RELAXED, __HIP_MEMORY_SCOPE_AGENT); }
.LBB0_425:
	s_or_b64 exec, exec, s[12:13]
	v_or_b32_e32 v112, 16, v148
	v_ashrrev_i32_e32 v113, 31, v112
	v_lshlrev_b64 v[114:115], 11, v[112:113]
	v_lshl_add_u64 v[118:119], v[114:115], 0, v[146:147]
	v_lshlrev_b64 v[120:121], 2, v[118:119]
	v_lshl_add_u64 v[122:123], s[52:53], 0, v[120:121]
	v_lshlrev_b64 v[118:119], 1, v[118:119]
	s_waitcnt vmcnt(20)
	v_pk_fma_f32 v[110:111], v[110:111], 0.5, v[182:183] op_sel_hi:[1,0,1]
	v_pk_fma_f32 v[108:109], v[108:109], 0.5, v[180:181] op_sel_hi:[1,0,1]
	v_lshl_add_u64 v[114:115], s[30:31], 0, v[120:121]
	global_store_dwordx4 v[114:115], v[108:111], off
	v_cvt_pk_bf16_f32 v116, v108, v109
	v_cvt_pk_bf16_f32 v117, v110, v111
	v_mul_f32_e32 v109, v109, v109
	v_lshl_add_u64 v[120:121], s[40:41], 0, v[118:119]
	v_fmac_f32_e32 v109, v108, v108
	v_mul_f32_e32 v108, v111, v111
	global_store_dwordx2 v[120:121], v[116:117], off
	v_fmac_f32_e32 v108, v110, v110
	v_add_f32_e32 v116, v109, v108
	v_pk_fma_f32 v[106:107], v[106:107], 0.5, v[190:191] op_sel_hi:[1,0,1]
	v_pk_fma_f32 v[104:105], v[104:105], 0.5, v[188:189] op_sel_hi:[1,0,1]
	global_store_dwordx4 v[114:115], v[104:107], off offset:16
	v_cvt_pk_bf16_f32 v108, v104, v105
	v_or_b32_e32 v110, 8, v118
	v_mul_f32_e32 v105, v105, v105
	v_mov_b32_e32 v111, v119
	v_fmac_f32_e32 v105, v104, v104
	v_mul_f32_e32 v104, v107, v107
	v_cvt_pk_bf16_f32 v109, v106, v107
	v_lshl_add_u64 v[110:111], s[40:41], 0, v[110:111]
	v_fmac_f32_e32 v104, v106, v106
	global_store_dwordx2 v[110:111], v[108:109], off
	v_add_f32_e32 v104, v105, v104
	v_add_f32_e32 v108, v116, v104
	v_pk_fma_f32 v[102:103], v[102:103], 0.5, v[194:195] op_sel_hi:[1,0,1]
	v_pk_fma_f32 v[100:101], v[100:101], 0.5, v[192:193] op_sel_hi:[1,0,1]
	global_store_dwordx4 v[114:115], v[100:103], off offset:512
	v_cvt_pk_bf16_f32 v104, v100, v101
	v_or_b32_e32 v106, 0x100, v118
	v_mul_f32_e32 v101, v101, v101
	v_mov_b32_e32 v107, v119
	v_fmac_f32_e32 v101, v100, v100
	v_mul_f32_e32 v100, v103, v103
	v_cvt_pk_bf16_f32 v105, v102, v103
	v_lshl_add_u64 v[106:107], s[40:41], 0, v[106:107]
	v_fmac_f32_e32 v100, v102, v102
	global_store_dwordx2 v[106:107], v[104:105], off
	v_add_f32_e32 v100, v101, v100
	v_add_f32_e32 v104, v108, v100
	v_or_b32_e32 v118, 0x108, v118
	v_pk_fma_f32 v[98:99], v[98:99], 0.5, v[198:199] op_sel_hi:[1,0,1]
	v_pk_fma_f32 v[96:97], v[96:97], 0.5, v[196:197] op_sel_hi:[1,0,1]
	v_mov_b32_e32 v230, 0x120000
	v_lshl_add_u64 v[228:229], v[232:233], 0, v[230:231]
	global_load_dwordx4 v[180:183], v[228:229], off
	global_load_dwordx4 v[188:191], v[228:229], off offset:16
	global_load_dwordx4 v[192:195], v[228:229], off offset:512
	global_load_dwordx4 v[196:199], v[228:229], off offset:528
	global_store_dwordx4 v[114:115], v[96:99], off offset:528
	v_cvt_pk_bf16_f32 v100, v96, v97
	v_cvt_pk_bf16_f32 v101, v98, v99
	v_mul_f32_e32 v97, v97, v97
	v_fmac_f32_e32 v97, v96, v96
	v_mul_f32_e32 v96, v99, v99
	v_fmac_f32_e32 v96, v98, v98
	v_add_f32_e32 v96, v97, v96
	v_add_f32_e32 v96, v104, v96
	v_mov_b32_e32 v97, v96
	s_nop 1
	v_permlane16_swap_b32 v96, v97
	v_lshl_add_u64 v[102:103], s[40:41], 0, v[118:119]
	v_add_f32_e32 v96, v96, v97
	v_mov_b32_e32 v97, v96
	global_store_dwordx2 v[102:103], v[100:101], off
	s_nop 1
	v_permlane32_swap_b32 v96, v97
	s_and_saveexec_b64 s[12:13], s[2:3]
	s_cbranch_execz .LBB0_427
	v_lshl_add_u64 v[98:99], v[112:113], 2, s[90:91]
	v_add_f32_e32 v96, v96, v97
	global_atomic_add_f32 v[98:99], v96, off
.LBB0_427:
	s_or_b64 exec, exec, s[12:13]
	v_or_b32_e32 v96, 32, v148
	v_ashrrev_i32_e32 v97, 31, v96
	v_lshlrev_b64 v[98:99], 11, v[96:97]
	v_lshl_add_u64 v[102:103], v[98:99], 0, v[146:147]
	v_lshlrev_b64 v[104:105], 2, v[102:103]
	v_lshl_add_u64 v[106:107], s[52:53], 0, v[104:105]
	v_lshlrev_b64 v[102:103], 1, v[102:103]
	s_waitcnt vmcnt(28)
	v_pk_fma_f32 v[94:95], v[94:95], 0.5, v[202:203] op_sel_hi:[1,0,1]
	v_pk_fma_f32 v[92:93], v[92:93], 0.5, v[200:201] op_sel_hi:[1,0,1]
	v_lshl_add_u64 v[98:99], s[30:31], 0, v[104:105]
	global_store_dwordx4 v[98:99], v[92:95], off
	v_cvt_pk_bf16_f32 v100, v92, v93
	v_cvt_pk_bf16_f32 v101, v94, v95
	v_mul_f32_e32 v93, v93, v93
	v_lshl_add_u64 v[104:105], s[40:41], 0, v[102:103]
	v_fmac_f32_e32 v93, v92, v92
	v_mul_f32_e32 v92, v95, v95
	global_store_dwordx2 v[104:105], v[100:101], off
	v_fmac_f32_e32 v92, v94, v94
	v_add_f32_e32 v100, v93, v92
	v_pk_fma_f32 v[90:91], v[90:91], 0.5, v[206:207] op_sel_hi:[1,0,1]
	v_pk_fma_f32 v[88:89], v[88:89], 0.5, v[204:205] op_sel_hi:[1,0,1]
	global_store_dwordx4 v[98:99], v[88:91], off offset:16
	v_cvt_pk_bf16_f32 v92, v88, v89
	v_or_b32_e32 v94, 8, v102
	v_mul_f32_e32 v89, v89, v89
	v_mov_b32_e32 v95, v103
	v_fmac_f32_e32 v89, v88, v88
	v_mul_f32_e32 v88, v91, v91
	v_cvt_pk_bf16_f32 v93, v90, v91
	v_lshl_add_u64 v[94:95], s[40:41], 0, v[94:95]
	v_fmac_f32_e32 v88, v90, v90
	global_store_dwordx2 v[94:95], v[92:93], off
	v_add_f32_e32 v88, v89, v88
	v_add_f32_e32 v92, v100, v88
	v_pk_fma_f32 v[86:87], v[86:87], 0.5, v[210:211] op_sel_hi:[1,0,1]
	v_pk_fma_f32 v[84:85], v[84:85], 0.5, v[208:209] op_sel_hi:[1,0,1]
	global_store_dwordx4 v[98:99], v[84:87], off offset:512
	v_cvt_pk_bf16_f32 v88, v84, v85
	v_or_b32_e32 v90, 0x100, v102
	v_mul_f32_e32 v85, v85, v85
	v_mov_b32_e32 v91, v103
	v_fmac_f32_e32 v85, v84, v84
	v_mul_f32_e32 v84, v87, v87
	v_cvt_pk_bf16_f32 v89, v86, v87
	v_lshl_add_u64 v[90:91], s[40:41], 0, v[90:91]
	v_fmac_f32_e32 v84, v86, v86
	global_store_dwordx2 v[90:91], v[88:89], off
	v_add_f32_e32 v84, v85, v84
	v_add_f32_e32 v88, v92, v84
	v_or_b32_e32 v102, 0x108, v102
	v_pk_fma_f32 v[82:83], v[82:83], 0.5, v[214:215] op_sel_hi:[1,0,1]
	v_pk_fma_f32 v[80:81], v[80:81], 0.5, v[212:213] op_sel_hi:[1,0,1]
	v_mov_b32_e32 v230, 0x140000
	v_lshl_add_u64 v[228:229], v[232:233], 0, v[230:231]
	global_load_dwordx4 v[200:203], v[228:229], off
	global_load_dwordx4 v[204:207], v[228:229], off offset:16
	global_load_dwordx4 v[208:211], v[228:229], off offset:512
	global_load_dwordx4 v[212:215], v[228:229], off offset:528
	global_store_dwordx4 v[98:99], v[80:83], off offset:528
	v_cvt_pk_bf16_f32 v84, v80, v81
	v_cvt_pk_bf16_f32 v85, v82, v83
	v_mul_f32_e32 v81, v81, v81
	v_fmac_f32_e32 v81, v80, v80
	v_mul_f32_e32 v80, v83, v83
	v_fmac_f32_e32 v80, v82, v82
	v_add_f32_e32 v80, v81, v80
	v_add_f32_e32 v80, v88, v80
	v_mov_b32_e32 v81, v80
	s_nop 1
	v_permlane16_swap_b32 v80, v81
	v_lshl_add_u64 v[86:87], s[40:41], 0, v[102:103]
	v_add_f32_e32 v80, v80, v81
	v_mov_b32_e32 v81, v80
	global_store_dwordx2 v[86:87], v[84:85], off
	s_nop 1
	v_permlane32_swap_b32 v80, v81
	s_and_saveexec_b64 s[12:13], s[2:3]
	s_cbranch_execz .LBB0_429
	v_lshl_add_u64 v[82:83], v[96:97], 2, s[90:91]
	v_add_f32_e32 v80, v80, v81
	global_atomic_add_f32 v[82:83], v80, off
; __device__ __forceinline__ unsigned pk2(float lo, float hi) { f32x2_t v = {lo, hi}; bf16x2_t b = __builtin_convertvector(v, bf16x2_t); return __builtin_bit_cast(unsigned, b); }
; __device__ __forceinline__ float xor16_sum(float v) { float a = v, b = v; swap16(a, b); return a + b; }
; __device__ __forceinline__ float xor32_sum(float v) { float a = v, b = v; swap32(a, b); return a + b; }
;     __device__ __forceinline__ void operator()(const f32x4 (&acc)[2][2][4][2], const Unit& u, int wr, int wc, int fr, int fq) const {
;     ...
;                 const int row = row0 + ai * HALF + m * 16; float sq = 0.f;
; #pragma unroll
;                 for (int bj = 0; bj < 2; ++bj)
; #pragma unroll
;                     for (int n = 0; n < 2; ++n) {
;                         const size_t idx = (size_t)row * ldc + u.pn * BM + bj * HALF + wc * 32 + 8 * fq + 4 * n;
;                         const f32x4 b = *(const f32x4*)(base + idx);
;                         const f32x4 v = b + acc[ai][bj][m][n] * alpha;
;                         *(f32x4*)(out + idx) = v;
;                         if (NORM) { u32x2 w; w.x = pk2(v[0], v[1]); w.y = pk2(v[2], v[3]); *(u32x2*)(xb + idx) = w; sq += (v[0] * v[0] + v[1] * v[1]) + (v[2] * v[2] + v[3] * v[3]); }
;                     }
;                 if (NORM) { sq = xor16_sum(sq); sq = xor32_sum(sq); if (fq == 0) __hip_atomic_fetch_add(ss + row, sq, __ATOMIC_RELAXED, __HIP_MEMORY_SCOPE_AGENT); }
.LBB0_429:
	s_or_b64 exec, exec, s[12:13]
	v_or_b32_e32 v80, 48, v148
	v_ashrrev_i32_e32 v81, 31, v80
	v_lshlrev_b64 v[82:83], 11, v[80:81]
	v_lshl_add_u64 v[86:87], v[82:83], 0, v[146:147]
	v_lshlrev_b64 v[88:89], 2, v[86:87]
	v_lshl_add_u64 v[90:91], s[52:53], 0, v[88:89]
	v_lshlrev_b64 v[86:87], 1, v[86:87]
	s_waitcnt vmcnt(36)
	v_pk_fma_f32 v[78:79], v[78:79], 0.5, v[218:219] op_sel_hi:[1,0,1]
	v_pk_fma_f32 v[76:77], v[76:77], 0.5, v[216:217] op_sel_hi:[1,0,1]
	v_lshl_add_u64 v[82:83], s[30:31], 0, v[88:89]
	global_store_dwordx4 v[82:83], v[76:79], off
	v_cvt_pk_bf16_f32 v84, v76, v77
	v_cvt_pk_bf16_f32 v85, v78, v79
	v_mul_f32_e32 v77, v77, v77
	v_lshl_add_u64 v[88:89], s[40:41], 0, v[86:87]
	v_fmac_f32_e32 v77, v76, v76
	v_mul_f32_e32 v76, v79, v79
	global_store_dwordx2 v[88:89], v[84:85], off
	v_fmac_f32_e32 v76, v78, v78
	v_add_f32_e32 v84, v77, v76
	v_pk_fma_f32 v[74:75], v[74:75], 0.5, v[222:223] op_sel_hi:[1,0,1]
	v_pk_fma_f32 v[72:73], v[72:73], 0.5, v[220:221] op_sel_hi:[1,0,1]
	global_store_dwordx4 v[82:83], v[72:75], off offset:16
	v_cvt_pk_bf16_f32 v76, v72, v73
	v_or_b32_e32 v78, 8, v86
	v_mul_f32_e32 v73, v73, v73
	v_mov_b32_e32 v79, v87
	v_fmac_f32_e32 v73, v72, v72
	v_mul_f32_e32 v72, v75, v75
	v_cvt_pk_bf16_f32 v77, v74, v75
	v_lshl_add_u64 v[78:79], s[40:41], 0, v[78:79]
	v_fmac_f32_e32 v72, v74, v74
	global_store_dwordx2 v[78:79], v[76:77], off
	v_add_f32_e32 v72, v73, v72
	v_add_f32_e32 v76, v84, v72
	v_pk_fma_f32 v[70:71], v[70:71], 0.5, v[226:227] op_sel_hi:[1,0,1]
	v_pk_fma_f32 v[68:69], v[68:69], 0.5, v[224:225] op_sel_hi:[1,0,1]
	global_store_dwordx4 v[82:83], v[68:71], off offset:512
	v_cvt_pk_bf16_f32 v72, v68, v69
	v_or_b32_e32 v74, 0x100, v86
	v_mul_f32_e32 v69, v69, v69
	v_mov_b32_e32 v75, v87
	v_fmac_f32_e32 v69, v68, v68
	v_mul_f32_e32 v68, v71, v71
	v_cvt_pk_bf16_f32 v73, v70, v71
	v_lshl_add_u64 v[74:75], s[40:41], 0, v[74:75]
	v_fmac_f32_e32 v68, v70, v70
	global_store_dwordx2 v[74:75], v[72:73], off
	v_add_f32_e32 v68, v69, v68
	v_add_f32_e32 v72, v76, v68
	v_or_b32_e32 v86, 0x108, v86
	v_pk_fma_f32 v[66:67], v[66:67], 0.5, v[236:237] op_sel_hi:[1,0,1]
	v_pk_fma_f32 v[64:65], v[64:65], 0.5, v[234:235] op_sel_hi:[1,0,1]
	v_mov_b32_e32 v230, 0x160000
	v_lshl_add_u64 v[228:229], v[232:233], 0, v[230:231]
	global_load_dwordx4 v[216:219], v[228:229], off
	global_load_dwordx4 v[220:223], v[228:229], off offset:16
	global_load_dwordx4 v[224:227], v[228:229], off offset:512
	global_load_dwordx4 v[234:237], v[228:229], off offset:528
	global_store_dwordx4 v[82:83], v[64:67], off offset:528
	v_cvt_pk_bf16_f32 v68, v64, v65
	v_cvt_pk_bf16_f32 v69, v66, v67
	v_mul_f32_e32 v65, v65, v65
	v_fmac_f32_e32 v65, v64, v64
	v_mul_f32_e32 v64, v67, v67
	v_fmac_f32_e32 v64, v66, v66
	v_add_f32_e32 v64, v65, v64
	v_add_f32_e32 v64, v72, v64
	v_mov_b32_e32 v65, v64
	s_nop 1
	v_permlane16_swap_b32 v64, v65
	v_lshl_add_u64 v[70:71], s[40:41], 0, v[86:87]
	v_add_f32_e32 v64, v64, v65
	v_mov_b32_e32 v65, v64
	global_store_dwordx2 v[70:71], v[68:69], off
	s_nop 1
	v_permlane32_swap_b32 v64, v65
	s_and_saveexec_b64 s[12:13], s[2:3]
	s_cbranch_execz .LBB0_431
	v_lshl_add_u64 v[66:67], v[80:81], 2, s[90:91]
	v_add_f32_e32 v64, v64, v65
	global_atomic_add_f32 v[66:67], v64, off
.LBB0_431:
	s_or_b64 exec, exec, s[12:13]
	v_add_u32_e32 v64, 0x80, v148
	v_ashrrev_i32_e32 v65, 31, v64
	v_lshlrev_b64 v[66:67], 11, v[64:65]
	v_lshl_add_u64 v[70:71], v[66:67], 0, v[146:147]
	v_lshlrev_b64 v[72:73], 2, v[70:71]
	v_lshl_add_u64 v[74:75], s[52:53], 0, v[72:73]
	v_lshlrev_b64 v[70:71], 1, v[70:71]
	s_waitcnt vmcnt(38)
	v_pk_fma_f32 v[62:63], v[62:63], 0.5, v[166:167] op_sel_hi:[1,0,1]
	v_pk_fma_f32 v[60:61], v[60:61], 0.5, v[164:165] op_sel_hi:[1,0,1]
	v_lshl_add_u64 v[66:67], s[30:31], 0, v[72:73]
	global_store_dwordx4 v[66:67], v[60:63], off
	v_cvt_pk_bf16_f32 v68, v60, v61
	v_cvt_pk_bf16_f32 v69, v62, v63
	v_mul_f32_e32 v61, v61, v61
	v_lshl_add_u64 v[72:73], s[40:41], 0, v[70:71]
	v_fmac_f32_e32 v61, v60, v60
	v_mul_f32_e32 v60, v63, v63
	global_store_dwordx2 v[72:73], v[68:69], off
	v_fmac_f32_e32 v60, v62, v62
	v_add_f32_e32 v68, v61, v60
	v_pk_fma_f32 v[58:59], v[58:59], 0.5, v[170:171] op_sel_hi:[1,0,1]
	v_pk_fma_f32 v[56:57], v[56:57], 0.5, v[168:169] op_sel_hi:[1,0,1]
	global_store_dwordx4 v[66:67], v[56:59], off offset:16
	v_cvt_pk_bf16_f32 v60, v56, v57
	v_or_b32_e32 v62, 8, v70
	v_mul_f32_e32 v57, v57, v57
	v_mov_b32_e32 v63, v71
	v_fmac_f32_e32 v57, v56, v56
	v_mul_f32_e32 v56, v59, v59
	v_cvt_pk_bf16_f32 v61, v58, v59
	v_lshl_add_u64 v[62:63], s[40:41], 0, v[62:63]
	v_fmac_f32_e32 v56, v58, v58
	global_store_dwordx2 v[62:63], v[60:61], off
	v_add_f32_e32 v56, v57, v56
	v_add_f32_e32 v60, v68, v56
	v_pk_fma_f32 v[54:55], v[54:55], 0.5, v[174:175] op_sel_hi:[1,0,1]
	v_pk_fma_f32 v[52:53], v[52:53], 0.5, v[172:173] op_sel_hi:[1,0,1]
	global_store_dwordx4 v[66:67], v[52:55], off offset:512
	v_cvt_pk_bf16_f32 v56, v52, v53
	v_or_b32_e32 v58, 0x100, v70
	v_mul_f32_e32 v53, v53, v53
	v_mov_b32_e32 v59, v71
	v_fmac_f32_e32 v53, v52, v52
	v_mul_f32_e32 v52, v55, v55
	v_cvt_pk_bf16_f32 v57, v54, v55
	v_lshl_add_u64 v[58:59], s[40:41], 0, v[58:59]
	v_fmac_f32_e32 v52, v54, v54
	global_store_dwordx2 v[58:59], v[56:57], off
	v_add_f32_e32 v52, v53, v52
	v_add_f32_e32 v56, v60, v52
	v_or_b32_e32 v70, 0x108, v70
	v_pk_fma_f32 v[50:51], v[50:51], 0.5, v[178:179] op_sel_hi:[1,0,1]
	v_pk_fma_f32 v[48:49], v[48:49], 0.5, v[176:177] op_sel_hi:[1,0,1]
	global_store_dwordx4 v[66:67], v[48:51], off offset:528
	v_cvt_pk_bf16_f32 v52, v48, v49
	v_cvt_pk_bf16_f32 v53, v50, v51
	v_mul_f32_e32 v49, v49, v49
	v_fmac_f32_e32 v49, v48, v48
	v_mul_f32_e32 v48, v51, v51
	v_fmac_f32_e32 v48, v50, v50
	v_add_f32_e32 v48, v49, v48
	v_add_f32_e32 v48, v56, v48
	v_mov_b32_e32 v49, v48
	s_nop 1
	v_permlane16_swap_b32 v49, v48
	v_lshl_add_u64 v[54:55], s[40:41], 0, v[70:71]
	v_add_f32_e32 v48, v49, v48
	v_mov_b32_e32 v49, v48
	global_store_dwordx2 v[54:55], v[52:53], off
	s_nop 1
	v_permlane32_swap_b32 v49, v48
	s_and_saveexec_b64 s[12:13], s[2:3]
	s_cbranch_execz .LBB0_433
	v_lshl_add_u64 v[50:51], v[64:65], 2, s[90:91]
	v_add_f32_e32 v48, v49, v48
	global_atomic_add_f32 v[50:51], v48, off
; __device__ __forceinline__ unsigned pk2(float lo, float hi) { f32x2_t v = {lo, hi}; bf16x2_t b = __builtin_convertvector(v, bf16x2_t); return __builtin_bit_cast(unsigned, b); }
; __device__ __forceinline__ float xor16_sum(float v) { float a = v, b = v; swap16(a, b); return a + b; }
; __device__ __forceinline__ float xor32_sum(float v) { float a = v, b = v; swap32(a, b); return a + b; }
;     __device__ __forceinline__ void operator()(const f32x4 (&acc)[2][2][4][2], const Unit& u, int wr, int wc, int fr, int fq) const {
;     ...
;                 const int row = row0 + ai * HALF + m * 16; float sq = 0.f;
; #pragma unroll
;                 for (int bj = 0; bj < 2; ++bj)
; #pragma unroll
;                     for (int n = 0; n < 2; ++n) {
;                         const size_t idx = (size_t)row * ldc + u.pn * BM + bj * HALF + wc * 32 + 8 * fq + 4 * n;
;                         const f32x4 b = *(const f32x4*)(base + idx);
;                         const f32x4 v = b + acc[ai][bj][m][n] * alpha;
;                         *(f32x4*)(out + idx) = v;
;                         if (NORM) { u32x2 w; w.x = pk2(v[0], v[1]); w.y = pk2(v[2], v[3]); *(u32x2*)(xb + idx) = w; sq += (v[0] * v[0] + v[1] * v[1]) + (v[2] * v[2] + v[3] * v[3]); }
;                     }
;                 if (NORM) { sq = xor16_sum(sq); sq = xor32_sum(sq); if (fq == 0) __hip_atomic_fetch_add(ss + row, sq, __ATOMIC_RELAXED, __HIP_MEMORY_SCOPE_AGENT); }
.LBB0_433:
	s_or_b64 exec, exec, s[12:13]
	v_add_u32_e32 v48, 0x90, v148
	v_ashrrev_i32_e32 v49, 31, v48
	v_lshlrev_b64 v[50:51], 11, v[48:49]
	v_lshl_add_u64 v[54:55], v[50:51], 0, v[146:147]
	v_lshlrev_b64 v[56:57], 2, v[54:55]
	v_lshl_add_u64 v[58:59], s[52:53], 0, v[56:57]
	v_lshlrev_b64 v[54:55], 1, v[54:55]
	s_waitcnt vmcnt(34)
	v_pk_fma_f32 v[46:47], v[46:47], 0.5, v[182:183] op_sel_hi:[1,0,1]
	v_pk_fma_f32 v[44:45], v[44:45], 0.5, v[180:181] op_sel_hi:[1,0,1]
	v_lshl_add_u64 v[50:51], s[30:31], 0, v[56:57]
	global_store_dwordx4 v[50:51], v[44:47], off
	v_cvt_pk_bf16_f32 v52, v44, v45
	v_cvt_pk_bf16_f32 v53, v46, v47
	v_mul_f32_e32 v45, v45, v45
	v_lshl_add_u64 v[56:57], s[40:41], 0, v[54:55]
	v_fmac_f32_e32 v45, v44, v44
	v_mul_f32_e32 v44, v47, v47
	global_store_dwordx2 v[56:57], v[52:53], off
	v_fmac_f32_e32 v44, v46, v46
	v_add_f32_e32 v52, v45, v44
	v_pk_fma_f32 v[42:43], v[42:43], 0.5, v[190:191] op_sel_hi:[1,0,1]
	v_pk_fma_f32 v[40:41], v[40:41], 0.5, v[188:189] op_sel_hi:[1,0,1]
	global_store_dwordx4 v[50:51], v[40:43], off offset:16
	v_cvt_pk_bf16_f32 v44, v40, v41
	v_or_b32_e32 v46, 8, v54
	v_mul_f32_e32 v41, v41, v41
	v_mov_b32_e32 v47, v55
	v_fmac_f32_e32 v41, v40, v40
	v_mul_f32_e32 v40, v43, v43
	v_cvt_pk_bf16_f32 v45, v42, v43
	v_lshl_add_u64 v[46:47], s[40:41], 0, v[46:47]
	v_fmac_f32_e32 v40, v42, v42
	global_store_dwordx2 v[46:47], v[44:45], off
	v_add_f32_e32 v40, v41, v40
	v_add_f32_e32 v44, v52, v40
	v_pk_fma_f32 v[38:39], v[38:39], 0.5, v[194:195] op_sel_hi:[1,0,1]
	v_pk_fma_f32 v[36:37], v[36:37], 0.5, v[192:193] op_sel_hi:[1,0,1]
	global_store_dwordx4 v[50:51], v[36:39], off offset:512
	v_cvt_pk_bf16_f32 v40, v36, v37
	v_or_b32_e32 v42, 0x100, v54
	v_mul_f32_e32 v37, v37, v37
	v_mov_b32_e32 v43, v55
	v_fmac_f32_e32 v37, v36, v36
	v_mul_f32_e32 v36, v39, v39
	v_cvt_pk_bf16_f32 v41, v38, v39
	v_lshl_add_u64 v[42:43], s[40:41], 0, v[42:43]
	v_fmac_f32_e32 v36, v38, v38
	global_store_dwordx2 v[42:43], v[40:41], off
	v_add_f32_e32 v36, v37, v36
	v_add_f32_e32 v40, v44, v36
	v_or_b32_e32 v54, 0x108, v54
	v_pk_fma_f32 v[34:35], v[34:35], 0.5, v[198:199] op_sel_hi:[1,0,1]
	v_pk_fma_f32 v[32:33], v[32:33], 0.5, v[196:197] op_sel_hi:[1,0,1]
	global_store_dwordx4 v[50:51], v[32:35], off offset:528
	v_cvt_pk_bf16_f32 v36, v32, v33
	v_cvt_pk_bf16_f32 v37, v34, v35
	v_mul_f32_e32 v33, v33, v33
	v_fmac_f32_e32 v33, v32, v32
	v_mul_f32_e32 v32, v35, v35
	v_fmac_f32_e32 v32, v34, v34
	v_add_f32_e32 v32, v33, v32
	v_add_f32_e32 v32, v40, v32
	v_mov_b32_e32 v33, v32
	s_nop 1
	v_permlane16_swap_b32 v32, v33
	v_lshl_add_u64 v[38:39], s[40:41], 0, v[54:55]
	v_add_f32_e32 v32, v32, v33
	v_mov_b32_e32 v33, v32
	global_store_dwordx2 v[38:39], v[36:37], off
	s_nop 1
	v_permlane32_swap_b32 v32, v33
	s_and_saveexec_b64 s[12:13], s[2:3]
	s_cbranch_execz .LBB0_435
	v_lshl_add_u64 v[34:35], v[48:49], 2, s[90:91]
	v_add_f32_e32 v32, v32, v33
	global_atomic_add_f32 v[34:35], v32, off
; __device__ __forceinline__ unsigned pk2(float lo, float hi) { f32x2_t v = {lo, hi}; bf16x2_t b = __builtin_convertvector(v, bf16x2_t); return __builtin_bit_cast(unsigned, b); }
; __device__ __forceinline__ float xor16_sum(float v) { float a = v, b = v; swap16(a, b); return a + b; }
; __device__ __forceinline__ float xor32_sum(float v) { float a = v, b = v; swap32(a, b); return a + b; }
;     __device__ __forceinline__ void operator()(const f32x4 (&acc)[2][2][4][2], const Unit& u, int wr, int wc, int fr, int fq) const {
;     ...
;                 const int row = row0 + ai * HALF + m * 16; float sq = 0.f;
; #pragma unroll
;                 for (int bj = 0; bj < 2; ++bj)
; #pragma unroll
;                     for (int n = 0; n < 2; ++n) {
;                         const size_t idx = (size_t)row * ldc + u.pn * BM + bj * HALF + wc * 32 + 8 * fq + 4 * n;
;                         const f32x4 b = *(const f32x4*)(base + idx);
;                         const f32x4 v = b + acc[ai][bj][m][n] * alpha;
;                         *(f32x4*)(out + idx) = v;
;                         if (NORM) { u32x2 w; w.x = pk2(v[0], v[1]); w.y = pk2(v[2], v[3]); *(u32x2*)(xb + idx) = w; sq += (v[0] * v[0] + v[1] * v[1]) + (v[2] * v[2] + v[3] * v[3]); }
;                     }
;                 if (NORM) { sq = xor16_sum(sq); sq = xor32_sum(sq); if (fq == 0) __hip_atomic_fetch_add(ss + row, sq, __ATOMIC_RELAXED, __HIP_MEMORY_SCOPE_AGENT); }
.LBB0_435:
	s_or_b64 exec, exec, s[12:13]
	v_add_u32_e32 v32, 0xa0, v148
	v_ashrrev_i32_e32 v33, 31, v32
	v_lshlrev_b64 v[34:35], 11, v[32:33]
	v_lshl_add_u64 v[38:39], v[34:35], 0, v[146:147]
	v_lshlrev_b64 v[40:41], 2, v[38:39]
	v_lshl_add_u64 v[42:43], s[52:53], 0, v[40:41]
	v_lshlrev_b64 v[38:39], 1, v[38:39]
	s_waitcnt vmcnt(30)
	v_pk_fma_f32 v[30:31], v[30:31], 0.5, v[202:203] op_sel_hi:[1,0,1]
	v_pk_fma_f32 v[28:29], v[28:29], 0.5, v[200:201] op_sel_hi:[1,0,1]
	v_lshl_add_u64 v[34:35], s[30:31], 0, v[40:41]
	global_store_dwordx4 v[34:35], v[28:31], off
	v_cvt_pk_bf16_f32 v36, v28, v29
	v_cvt_pk_bf16_f32 v37, v30, v31
	v_mul_f32_e32 v29, v29, v29
	v_lshl_add_u64 v[40:41], s[40:41], 0, v[38:39]
	v_fmac_f32_e32 v29, v28, v28
	v_mul_f32_e32 v28, v31, v31
	global_store_dwordx2 v[40:41], v[36:37], off
	v_fmac_f32_e32 v28, v30, v30
	v_add_f32_e32 v36, v29, v28
	v_pk_fma_f32 v[26:27], v[26:27], 0.5, v[206:207] op_sel_hi:[1,0,1]
	v_pk_fma_f32 v[24:25], v[24:25], 0.5, v[204:205] op_sel_hi:[1,0,1]
	global_store_dwordx4 v[34:35], v[24:27], off offset:16
	v_cvt_pk_bf16_f32 v28, v24, v25
	v_or_b32_e32 v30, 8, v38
	v_mul_f32_e32 v25, v25, v25
	v_mov_b32_e32 v31, v39
	v_fmac_f32_e32 v25, v24, v24
	v_mul_f32_e32 v24, v27, v27
	v_cvt_pk_bf16_f32 v29, v26, v27
	v_lshl_add_u64 v[30:31], s[40:41], 0, v[30:31]
	v_fmac_f32_e32 v24, v26, v26
	global_store_dwordx2 v[30:31], v[28:29], off
	v_add_f32_e32 v24, v25, v24
	v_add_f32_e32 v28, v36, v24
	v_pk_fma_f32 v[22:23], v[22:23], 0.5, v[210:211] op_sel_hi:[1,0,1]
	v_pk_fma_f32 v[20:21], v[20:21], 0.5, v[208:209] op_sel_hi:[1,0,1]
	global_store_dwordx4 v[34:35], v[20:23], off offset:512
	v_cvt_pk_bf16_f32 v24, v20, v21
	v_or_b32_e32 v26, 0x100, v38
	v_mul_f32_e32 v21, v21, v21
	v_mov_b32_e32 v27, v39
	v_fmac_f32_e32 v21, v20, v20
	v_mul_f32_e32 v20, v23, v23
	v_cvt_pk_bf16_f32 v25, v22, v23
	v_lshl_add_u64 v[26:27], s[40:41], 0, v[26:27]
	v_fmac_f32_e32 v20, v22, v22
	global_store_dwordx2 v[26:27], v[24:25], off
	v_add_f32_e32 v20, v21, v20
	v_add_f32_e32 v24, v28, v20
	v_or_b32_e32 v38, 0x108, v38
	v_pk_fma_f32 v[18:19], v[18:19], 0.5, v[214:215] op_sel_hi:[1,0,1]
	v_pk_fma_f32 v[16:17], v[16:17], 0.5, v[212:213] op_sel_hi:[1,0,1]
	global_store_dwordx4 v[34:35], v[16:19], off offset:528
	v_cvt_pk_bf16_f32 v20, v16, v17
	v_cvt_pk_bf16_f32 v21, v18, v19
	v_mul_f32_e32 v17, v17, v17
	v_fmac_f32_e32 v17, v16, v16
	v_mul_f32_e32 v16, v19, v19
	v_fmac_f32_e32 v16, v18, v18
	v_add_f32_e32 v16, v17, v16
	v_add_f32_e32 v16, v24, v16
	v_mov_b32_e32 v17, v16
	s_nop 1
	v_permlane16_swap_b32 v16, v17
	v_lshl_add_u64 v[22:23], s[40:41], 0, v[38:39]
	v_add_f32_e32 v16, v16, v17
	v_mov_b32_e32 v17, v16
	global_store_dwordx2 v[22:23], v[20:21], off
	s_nop 1
	v_permlane32_swap_b32 v16, v17
	s_and_saveexec_b64 s[12:13], s[2:3]
	s_cbranch_execz .LBB0_437
	v_lshl_add_u64 v[18:19], v[32:33], 2, s[90:91]
	v_add_f32_e32 v16, v16, v17
	global_atomic_add_f32 v[18:19], v16, off
.LBB0_437:
	s_or_b64 exec, exec, s[12:13]
	v_add_u32_e32 v16, 0xb0, v148
	v_ashrrev_i32_e32 v17, 31, v16
	v_lshlrev_b64 v[18:19], 11, v[16:17]
	v_lshl_add_u64 v[22:23], v[18:19], 0, v[146:147]
	v_lshlrev_b64 v[24:25], 2, v[22:23]
	v_lshl_add_u64 v[26:27], s[52:53], 0, v[24:25]
	v_lshlrev_b64 v[22:23], 1, v[22:23]
	s_waitcnt vmcnt(26)
	v_pk_fma_f32 v[14:15], v[14:15], 0.5, v[218:219] op_sel_hi:[1,0,1]
	v_pk_fma_f32 v[12:13], v[12:13], 0.5, v[216:217] op_sel_hi:[1,0,1]
	v_lshl_add_u64 v[18:19], s[30:31], 0, v[24:25]
	global_store_dwordx4 v[18:19], v[12:15], off
	v_cvt_pk_bf16_f32 v20, v12, v13
	v_cvt_pk_bf16_f32 v21, v14, v15
	v_mul_f32_e32 v13, v13, v13
	v_lshl_add_u64 v[24:25], s[40:41], 0, v[22:23]
	v_fmac_f32_e32 v13, v12, v12
	v_mul_f32_e32 v12, v15, v15
	global_store_dwordx2 v[24:25], v[20:21], off
	v_fmac_f32_e32 v12, v14, v14
	v_add_f32_e32 v20, v13, v12
	v_pk_fma_f32 v[10:11], v[10:11], 0.5, v[222:223] op_sel_hi:[1,0,1]
	v_pk_fma_f32 v[8:9], v[8:9], 0.5, v[220:221] op_sel_hi:[1,0,1]
	global_store_dwordx4 v[18:19], v[8:11], off offset:16
	v_cvt_pk_bf16_f32 v12, v8, v9
	v_or_b32_e32 v14, 8, v22
	v_mul_f32_e32 v9, v9, v9
	v_mov_b32_e32 v15, v23
	v_fmac_f32_e32 v9, v8, v8
	v_mul_f32_e32 v8, v11, v11
	v_cvt_pk_bf16_f32 v13, v10, v11
	v_lshl_add_u64 v[14:15], s[40:41], 0, v[14:15]
	v_fmac_f32_e32 v8, v10, v10
	global_store_dwordx2 v[14:15], v[12:13], off
	v_add_f32_e32 v8, v9, v8
	v_add_f32_e32 v12, v20, v8
	v_pk_fma_f32 v[6:7], v[6:7], 0.5, v[226:227] op_sel_hi:[1,0,1]
	v_pk_fma_f32 v[4:5], v[4:5], 0.5, v[224:225] op_sel_hi:[1,0,1]
	global_store_dwordx4 v[18:19], v[4:7], off offset:512
	v_cvt_pk_bf16_f32 v8, v4, v5
	v_or_b32_e32 v10, 0x100, v22
	v_mul_f32_e32 v5, v5, v5
	v_mov_b32_e32 v11, v23
	v_fmac_f32_e32 v5, v4, v4
	v_mul_f32_e32 v4, v7, v7
	v_cvt_pk_bf16_f32 v9, v6, v7
	v_lshl_add_u64 v[10:11], s[40:41], 0, v[10:11]
	v_fmac_f32_e32 v4, v6, v6
	global_store_dwordx2 v[10:11], v[8:9], off
	v_add_f32_e32 v4, v5, v4
	v_add_f32_e32 v8, v12, v4
	v_or_b32_e32 v22, 0x108, v22
	v_pk_fma_f32 v[2:3], v[2:3], 0.5, v[236:237] op_sel_hi:[1,0,1]
	v_pk_fma_f32 v[0:1], v[0:1], 0.5, v[234:235] op_sel_hi:[1,0,1]
	global_store_dwordx4 v[18:19], v[0:3], off offset:528
	v_cvt_pk_bf16_f32 v4, v0, v1
	v_cvt_pk_bf16_f32 v5, v2, v3
	v_mul_f32_e32 v1, v1, v1
	v_fmac_f32_e32 v1, v0, v0
	v_mul_f32_e32 v0, v3, v3
	v_fmac_f32_e32 v0, v2, v2
	v_add_f32_e32 v0, v1, v0
	v_add_f32_e32 v0, v8, v0
	v_mov_b32_e32 v1, v0
	s_nop 1
	v_permlane16_swap_b32 v0, v1
	v_lshl_add_u64 v[6:7], s[40:41], 0, v[22:23]
	v_add_f32_e32 v0, v0, v1
	v_mov_b32_e32 v1, v0
	global_store_dwordx2 v[6:7], v[4:5], off
	s_nop 1
	v_permlane32_swap_b32 v0, v1
	s_and_saveexec_b64 s[12:13], s[2:3]
	s_cbranch_execz .LBB0_439
	v_lshl_add_u64 v[2:3], v[16:17], 2, s[90:91]
	v_add_f32_e32 v0, v0, v1
	global_atomic_add_f32 v[2:3], v0, off

; __device__ __forceinline__ unsigned pk2(float lo, float hi) { f32x2_t v = {lo, hi}; bf16x2_t b = __builtin_convertvector(v, bf16x2_t); return __builtin_bit_cast(unsigned, b); }
; __device__ __forceinline__ float xor16_sum(float v) { float a = v, b = v; swap16(a, b); return a + b; }
; __device__ __forceinline__ float xor32_sum(float v) { float a = v, b = v; swap32(a, b); return a + b; }
;     __device__ __forceinline__ void operator()(const f32x4 (&acc)[2][2][4][2], const Unit& u, int wr, int wc, int fr, int fq) const {
;         const int row0 = u.pm * BM + wr * 64 + fr; constexpr int ldc = 2048; constexpr float alpha = 0.5f * ALPHA2;
;         bf16_t* const xb = (bf16_t*)(ws + XBOFF); __attribute__((address_space(1))) float* const ss = (__attribute__((address_space(1))) float*)(ws + SSOFF);
; #pragma unroll
;         for (int ai = 0; ai < 2; ++ai)
; #pragma unroll
;             for (int m = 0; m < 4; ++m) {
;                 const int row = row0 + ai * HALF + m * 16; float sq = 0.f;
; #pragma unroll
;                 for (int bj = 0; bj < 2; ++bj)
; #pragma unroll
;                     for (int n = 0; n < 2; ++n) {
;                         const size_t idx = (size_t)row * ldc + u.pn * BM + bj * HALF + wc * 32 + 8 * fq + 4 * n;
;                         const f32x4 b = *(const f32x4*)(base + idx);
;                         const f32x4 v = b + acc[ai][bj][m][n] * alpha;
;                         *(f32x4*)(out + idx) = v;
;                         if (NORM) { u32x2 w; w.x = pk2(v[0], v[1]); w.y = pk2(v[2], v[3]); *(u32x2*)(xb + idx) = w; sq += (v[0] * v[0] + v[1] * v[1]) + (v[2] * v[2] + v[3] * v[3]); }
;                     }
;                 if (NORM) { sq = xor16_sum(sq); sq = xor32_sum(sq); if (fq == 0) __hip_atomic_fetch_add(ss + row, sq, __ATOMIC_RELAXED, __HIP_MEMORY_SCOPE_AGENT); }
.LBB0_1208:
	v_lshl_add_u32 v148, s12, 8, v137
	s_lshl_b32 s12, s44, 8
	s_ashr_i32 s13, s12, 31
	v_ashrrev_i32_e32 v149, 31, v148
	v_mov_b32_e32 v147, s13
	v_or_b32_e32 v146, s12, v136
	v_lshlrev_b64 v[154:155], 11, v[148:149]
	v_lshl_add_u64 v[158:159], v[154:155], 0, v[146:147]
	v_lshl_add_u64 v[160:161], v[158:159], 2, s[30:31]
	v_mov_b32_e32 v232, v160
	v_mov_b32_e32 v233, v161
	v_mov_b32_e32 v231, 0
	v_mov_b32_e32 v230, 0x0
	v_lshl_add_u64 v[228:229], v[232:233], 0, v[230:231]
	global_load_dwordx4 v[164:167], v[228:229], off
	global_load_dwordx4 v[168:171], v[228:229], off offset:16
	global_load_dwordx4 v[172:175], v[228:229], off offset:512
	global_load_dwordx4 v[176:179], v[228:229], off offset:528
	v_mov_b32_e32 v230, 0x20000
	v_lshl_add_u64 v[228:229], v[232:233], 0, v[230:231]
	global_load_dwordx4 v[180:183], v[228:229], off
	global_load_dwordx4 v[188:191], v[228:229], off offset:16
	global_load_dwordx4 v[192:195], v[228:229], off offset:512
	global_load_dwordx4 v[196:199], v[228:229], off offset:528
	v_mov_b32_e32 v230, 0x40000
	v_lshl_add_u64 v[228:229], v[232:233], 0, v[230:231]
	global_load_dwordx4 v[200:203], v[228:229], off
	global_load_dwordx4 v[204:207], v[228:229], off offset:16
	global_load_dwordx4 v[208:211], v[228:229], off offset:512
	global_load_dwordx4 v[212:215], v[228:229], off offset:528
	v_mov_b32_e32 v230, 0x60000
	v_lshl_add_u64 v[228:229], v[232:233], 0, v[230:231]
	global_load_dwordx4 v[216:219], v[228:229], off
	global_load_dwordx4 v[220:223], v[228:229], off offset:16
	global_load_dwordx4 v[224:227], v[228:229], off offset:512
	global_load_dwordx4 v[234:237], v[228:229], off offset:528
	v_lshlrev_b64 v[158:159], 1, v[158:159]
	v_lshl_add_u64 v[162:163], s[6:7], 0, v[158:159]
	s_waitcnt vmcnt(12)
	v_pk_add_f32 v[126:127], v[126:127], v[166:167]
	v_pk_add_f32 v[124:125], v[124:125], v[164:165]
	v_cvt_pk_bf16_f32 v155, v126, v127
	v_cvt_pk_bf16_f32 v154, v124, v125
	global_store_dwordx4 v[160:161], v[124:127], off
	global_store_dwordx2 v[162:163], v[154:155], off
	v_or_b32_e32 v162, 8, v158
	v_mov_b32_e32 v163, v159
	v_lshl_add_u64 v[162:163], s[6:7], 0, v[162:163]
	v_mul_f32_e32 v125, v125, v125
	v_mul_f32_e32 v127, v127, v127
	v_fmac_f32_e32 v125, v124, v124
	v_fmac_f32_e32 v127, v126, v126
	v_add_f32_e32 v124, v125, v127
	v_pk_add_f32 v[122:123], v[122:123], v[170:171]
	v_pk_add_f32 v[120:121], v[120:121], v[168:169]
	v_cvt_pk_bf16_f32 v155, v122, v123
	v_cvt_pk_bf16_f32 v154, v120, v121
	global_store_dwordx4 v[160:161], v[120:123], off offset:16
	global_store_dwordx2 v[162:163], v[154:155], off
	v_or_b32_e32 v162, 0x100, v158
	v_mov_b32_e32 v163, v159
	v_lshl_add_u64 v[162:163], s[6:7], 0, v[162:163]
	v_mul_f32_e32 v121, v121, v121
	v_mul_f32_e32 v123, v123, v123
	v_fmac_f32_e32 v121, v120, v120
	v_fmac_f32_e32 v123, v122, v122
	v_add_f32_e32 v120, v121, v123
	v_add_f32_e32 v120, v124, v120
	v_or_b32_e32 v158, 0x108, v158
	v_lshl_add_u64 v[158:159], s[6:7], 0, v[158:159]
	v_pk_add_f32 v[118:119], v[118:119], v[174:175]
	v_pk_add_f32 v[116:117], v[116:117], v[172:173]
	v_cvt_pk_bf16_f32 v155, v118, v119
	v_cvt_pk_bf16_f32 v154, v116, v117
	global_store_dwordx4 v[160:161], v[116:119], off offset:512
	global_store_dwordx2 v[162:163], v[154:155], off
	v_mul_f32_e32 v117, v117, v117
	v_mul_f32_e32 v119, v119, v119
	v_fmac_f32_e32 v117, v116, v116
	v_fmac_f32_e32 v119, v118, v118
	v_add_f32_e32 v116, v117, v119
	v_add_f32_e32 v118, v120, v116
	v_pk_add_f32 v[114:115], v[114:115], v[178:179]
	v_pk_add_f32 v[112:113], v[112:113], v[176:177]
	v_mov_b32_e32 v230, 0x100000
	v_lshl_add_u64 v[228:229], v[232:233], 0, v[230:231]
	global_load_dwordx4 v[164:167], v[228:229], off
	global_load_dwordx4 v[168:171], v[228:229], off offset:16
	global_load_dwordx4 v[172:175], v[228:229], off offset:512
	global_load_dwordx4 v[176:179], v[228:229], off offset:528
	global_store_dwordx4 v[160:161], v[112:115], off offset:528
	v_cvt_pk_bf16_f32 v116, v112, v113
	v_cvt_pk_bf16_f32 v117, v114, v115
	v_mul_f32_e32 v113, v113, v113
	v_mul_f32_e32 v115, v115, v115
	v_fmac_f32_e32 v113, v112, v112
	v_fmac_f32_e32 v115, v114, v114
	v_add_f32_e32 v112, v113, v115
	v_add_f32_e32 v112, v118, v112
	v_mov_b32_e32 v113, v112
	s_nop 1
	v_permlane16_swap_b32 v113, v112
	global_store_dwordx2 v[158:159], v[116:117], off
	v_add_f32_e32 v112, v113, v112
	v_mov_b32_e32 v113, v112
	s_nop 1
	v_permlane32_swap_b32 v113, v112
	s_and_saveexec_b64 s[12:13], s[2:3]
	s_cbranch_execz .LBB0_1210
	v_lshl_add_u64 v[114:115], v[148:149], 2, s[8:9]
	v_add_f32_e32 v112, v113, v112
	global_atomic_add_f32 v[114:115], v112, off
; __device__ __forceinline__ unsigned pk2(float lo, float hi) { f32x2_t v = {lo, hi}; bf16x2_t b = __builtin_convertvector(v, bf16x2_t); return __builtin_bit_cast(unsigned, b); }
; __device__ __forceinline__ float xor16_sum(float v) { float a = v, b = v; swap16(a, b); return a + b; }
; __device__ __forceinline__ float xor32_sum(float v) { float a = v, b = v; swap32(a, b); return a + b; }
;     __device__ __forceinline__ void operator()(const f32x4 (&acc)[2][2][4][2], const Unit& u, int wr, int wc, int fr, int fq) const {
;     ...
;                 const int row = row0 + ai * HALF + m * 16; float sq = 0.f;
; #pragma unroll
;                 for (int bj = 0; bj < 2; ++bj)
; #pragma unroll
;                     for (int n = 0; n < 2; ++n) {
;                         const size_t idx = (size_t)row * ldc + u.pn * BM + bj * HALF + wc * 32 + 8 * fq + 4 * n;
;                         const f32x4 b = *(const f32x4*)(base + idx);
;                         const f32x4 v = b + acc[ai][bj][m][n] * alpha;
;                         *(f32x4*)(out + idx) = v;
;                         if (NORM) { u32x2 w; w.x = pk2(v[0], v[1]); w.y = pk2(v[2], v[3]); *(u32x2*)(xb + idx) = w; sq += (v[0] * v[0] + v[1] * v[1]) + (v[2] * v[2] + v[3] * v[3]); }
;                     }
;                 if (NORM) { sq = xor16_sum(sq); sq = xor32_sum(sq); if (fq == 0) __hip_atomic_fetch_add(ss + row, sq, __ATOMIC_RELAXED, __HIP_MEMORY_SCOPE_AGENT); }
.LBB0_1210:
	s_or_b64 exec, exec, s[12:13]
	v_or_b32_e32 v112, 16, v148
	v_ashrrev_i32_e32 v113, 31, v112
	v_lshlrev_b64 v[114:115], 11, v[112:113]
	v_lshl_add_u64 v[118:119], v[114:115], 0, v[146:147]
	v_lshl_add_u64 v[120:121], v[118:119], 2, s[30:31]
	v_lshlrev_b64 v[118:119], 1, v[118:119]
	v_lshl_add_u64 v[122:123], s[6:7], 0, v[118:119]
	s_waitcnt vmcnt(20)
	v_pk_add_f32 v[110:111], v[110:111], v[182:183]
	v_pk_add_f32 v[108:109], v[108:109], v[180:181]
	v_cvt_pk_bf16_f32 v115, v110, v111
	v_cvt_pk_bf16_f32 v114, v108, v109
	global_store_dwordx4 v[120:121], v[108:111], off
	global_store_dwordx2 v[122:123], v[114:115], off
	v_or_b32_e32 v122, 8, v118
	v_mov_b32_e32 v123, v119
	v_lshl_add_u64 v[122:123], s[6:7], 0, v[122:123]
	v_mul_f32_e32 v109, v109, v109
	v_mul_f32_e32 v111, v111, v111
	v_fmac_f32_e32 v109, v108, v108
	v_fmac_f32_e32 v111, v110, v110
	v_add_f32_e32 v108, v109, v111
	v_pk_add_f32 v[106:107], v[106:107], v[190:191]
	v_pk_add_f32 v[104:105], v[104:105], v[188:189]
	v_cvt_pk_bf16_f32 v115, v106, v107
	v_cvt_pk_bf16_f32 v114, v104, v105
	global_store_dwordx4 v[120:121], v[104:107], off offset:16
	global_store_dwordx2 v[122:123], v[114:115], off
	v_or_b32_e32 v122, 0x100, v118
	v_mov_b32_e32 v123, v119
	v_lshl_add_u64 v[122:123], s[6:7], 0, v[122:123]
	v_mul_f32_e32 v105, v105, v105
	v_mul_f32_e32 v107, v107, v107
	v_fmac_f32_e32 v105, v104, v104
	v_fmac_f32_e32 v107, v106, v106
	v_add_f32_e32 v104, v105, v107
	v_add_f32_e32 v104, v108, v104
	v_or_b32_e32 v118, 0x108, v118
	v_lshl_add_u64 v[118:119], s[6:7], 0, v[118:119]
	v_pk_add_f32 v[102:103], v[102:103], v[194:195]
	v_pk_add_f32 v[100:101], v[100:101], v[192:193]
	v_cvt_pk_bf16_f32 v115, v102, v103
	v_cvt_pk_bf16_f32 v114, v100, v101
	global_store_dwordx4 v[120:121], v[100:103], off offset:512
	global_store_dwordx2 v[122:123], v[114:115], off
	v_mul_f32_e32 v101, v101, v101
	v_mul_f32_e32 v103, v103, v103
	v_fmac_f32_e32 v101, v100, v100
	v_fmac_f32_e32 v103, v102, v102
	v_add_f32_e32 v100, v101, v103
	v_add_f32_e32 v102, v104, v100
	v_pk_add_f32 v[98:99], v[98:99], v[198:199]
	v_pk_add_f32 v[96:97], v[96:97], v[196:197]
	v_mov_b32_e32 v230, 0x120000
	v_lshl_add_u64 v[228:229], v[232:233], 0, v[230:231]
	global_load_dwordx4 v[180:183], v[228:229], off
	global_load_dwordx4 v[188:191], v[228:229], off offset:16
	global_load_dwordx4 v[192:195], v[228:229], off offset:512
	global_load_dwordx4 v[196:199], v[228:229], off offset:528
	global_store_dwordx4 v[120:121], v[96:99], off offset:528
	v_cvt_pk_bf16_f32 v100, v96, v97
	v_cvt_pk_bf16_f32 v101, v98, v99
	v_mul_f32_e32 v97, v97, v97
	v_mul_f32_e32 v99, v99, v99
	v_fmac_f32_e32 v97, v96, v96
	v_fmac_f32_e32 v99, v98, v98
	v_add_f32_e32 v96, v97, v99
	v_add_f32_e32 v96, v102, v96
	v_mov_b32_e32 v97, v96
	s_nop 1
	v_permlane16_swap_b32 v96, v97
	global_store_dwordx2 v[118:119], v[100:101], off
	v_add_f32_e32 v96, v96, v97
	v_mov_b32_e32 v97, v96
	s_nop 1
	v_permlane32_swap_b32 v96, v97
	s_and_saveexec_b64 s[12:13], s[2:3]
	s_cbranch_execz .LBB0_1212
	v_lshl_add_u64 v[98:99], v[112:113], 2, s[8:9]
	v_add_f32_e32 v96, v96, v97
	global_atomic_add_f32 v[98:99], v96, off
.LBB0_1212:
	s_or_b64 exec, exec, s[12:13]
	v_or_b32_e32 v96, 32, v148
	v_ashrrev_i32_e32 v97, 31, v96
	v_lshlrev_b64 v[98:99], 11, v[96:97]
	v_lshl_add_u64 v[102:103], v[98:99], 0, v[146:147]
	v_lshl_add_u64 v[104:105], v[102:103], 2, s[30:31]
	v_lshlrev_b64 v[102:103], 1, v[102:103]
	v_lshl_add_u64 v[106:107], s[6:7], 0, v[102:103]
	s_waitcnt vmcnt(28)
	v_pk_add_f32 v[94:95], v[94:95], v[202:203]
	v_pk_add_f32 v[92:93], v[92:93], v[200:201]
	v_cvt_pk_bf16_f32 v99, v94, v95
	v_cvt_pk_bf16_f32 v98, v92, v93
	global_store_dwordx4 v[104:105], v[92:95], off
	global_store_dwordx2 v[106:107], v[98:99], off
	v_or_b32_e32 v106, 8, v102
	v_mov_b32_e32 v107, v103
	v_lshl_add_u64 v[106:107], s[6:7], 0, v[106:107]
	v_mul_f32_e32 v93, v93, v93
	v_mul_f32_e32 v95, v95, v95
	v_fmac_f32_e32 v93, v92, v92
	v_fmac_f32_e32 v95, v94, v94
	v_add_f32_e32 v92, v93, v95
	v_pk_add_f32 v[90:91], v[90:91], v[206:207]
	v_pk_add_f32 v[88:89], v[88:89], v[204:205]
	v_cvt_pk_bf16_f32 v99, v90, v91
	v_cvt_pk_bf16_f32 v98, v88, v89
	global_store_dwordx4 v[104:105], v[88:91], off offset:16
	global_store_dwordx2 v[106:107], v[98:99], off
	v_or_b32_e32 v106, 0x100, v102
	v_mov_b32_e32 v107, v103
	v_lshl_add_u64 v[106:107], s[6:7], 0, v[106:107]
	v_mul_f32_e32 v89, v89, v89
	v_mul_f32_e32 v91, v91, v91
	v_fmac_f32_e32 v89, v88, v88
	v_fmac_f32_e32 v91, v90, v90
	v_add_f32_e32 v88, v89, v91
	v_add_f32_e32 v88, v92, v88
	v_or_b32_e32 v102, 0x108, v102
	v_lshl_add_u64 v[102:103], s[6:7], 0, v[102:103]
	v_pk_add_f32 v[86:87], v[86:87], v[210:211]
	v_pk_add_f32 v[84:85], v[84:85], v[208:209]
	v_cvt_pk_bf16_f32 v99, v86, v87
	v_cvt_pk_bf16_f32 v98, v84, v85
	global_store_dwordx4 v[104:105], v[84:87], off offset:512
	global_store_dwordx2 v[106:107], v[98:99], off
	v_mul_f32_e32 v85, v85, v85
	v_mul_f32_e32 v87, v87, v87
	v_fmac_f32_e32 v85, v84, v84
	v_fmac_f32_e32 v87, v86, v86
	v_add_f32_e32 v84, v85, v87
	v_add_f32_e32 v86, v88, v84
	v_pk_add_f32 v[82:83], v[82:83], v[214:215]
	v_pk_add_f32 v[80:81], v[80:81], v[212:213]
	v_mov_b32_e32 v230, 0x140000
	v_lshl_add_u64 v[228:229], v[232:233], 0, v[230:231]
	global_load_dwordx4 v[200:203], v[228:229], off
	global_load_dwordx4 v[204:207], v[228:229], off offset:16
	global_load_dwordx4 v[208:211], v[228:229], off offset:512
	global_load_dwordx4 v[212:215], v[228:229], off offset:528
	global_store_dwordx4 v[104:105], v[80:83], off offset:528
	v_cvt_pk_bf16_f32 v84, v80, v81
	v_cvt_pk_bf16_f32 v85, v82, v83
	v_mul_f32_e32 v81, v81, v81
	v_mul_f32_e32 v83, v83, v83
	v_fmac_f32_e32 v81, v80, v80
	v_fmac_f32_e32 v83, v82, v82
	v_add_f32_e32 v80, v81, v83
	v_add_f32_e32 v80, v86, v80
	v_mov_b32_e32 v81, v80
	s_nop 1
	v_permlane16_swap_b32 v80, v81
	global_store_dwordx2 v[102:103], v[84:85], off
	v_add_f32_e32 v80, v80, v81
	v_mov_b32_e32 v81, v80
	s_nop 1
	v_permlane32_swap_b32 v80, v81
	s_and_saveexec_b64 s[12:13], s[2:3]
	s_cbranch_execz .LBB0_1214
	v_lshl_add_u64 v[82:83], v[96:97], 2, s[8:9]
	v_add_f32_e32 v80, v80, v81
	global_atomic_add_f32 v[82:83], v80, off
; __device__ __forceinline__ unsigned pk2(float lo, float hi) { f32x2_t v = {lo, hi}; bf16x2_t b = __builtin_convertvector(v, bf16x2_t); return __builtin_bit_cast(unsigned, b); }
; __device__ __forceinline__ float xor16_sum(float v) { float a = v, b = v; swap16(a, b); return a + b; }
; __device__ __forceinline__ float xor32_sum(float v) { float a = v, b = v; swap32(a, b); return a + b; }
;     __device__ __forceinline__ void operator()(const f32x4 (&acc)[2][2][4][2], const Unit& u, int wr, int wc, int fr, int fq) const {
;     ...
;                 const int row = row0 + ai * HALF + m * 16; float sq = 0.f;
; #pragma unroll
;                 for (int bj = 0; bj < 2; ++bj)
; #pragma unroll
;                     for (int n = 0; n < 2; ++n) {
;                         const size_t idx = (size_t)row * ldc + u.pn * BM + bj * HALF + wc * 32 + 8 * fq + 4 * n;
;                         const f32x4 b = *(const f32x4*)(base + idx);
;                         const f32x4 v = b + acc[ai][bj][m][n] * alpha;
;                         *(f32x4*)(out + idx) = v;
;                         if (NORM) { u32x2 w; w.x = pk2(v[0], v[1]); w.y = pk2(v[2], v[3]); *(u32x2*)(xb + idx) = w; sq += (v[0] * v[0] + v[1] * v[1]) + (v[2] * v[2] + v[3] * v[3]); }
;                     }
;                 if (NORM) { sq = xor16_sum(sq); sq = xor32_sum(sq); if (fq == 0) __hip_atomic_fetch_add(ss + row, sq, __ATOMIC_RELAXED, __HIP_MEMORY_SCOPE_AGENT); }
.LBB0_1214:
	s_or_b64 exec, exec, s[12:13]
	v_or_b32_e32 v80, 48, v148
	v_ashrrev_i32_e32 v81, 31, v80
	v_lshlrev_b64 v[82:83], 11, v[80:81]
	v_lshl_add_u64 v[86:87], v[82:83], 0, v[146:147]
	v_lshl_add_u64 v[88:89], v[86:87], 2, s[30:31]
	v_lshlrev_b64 v[86:87], 1, v[86:87]
	v_lshl_add_u64 v[90:91], s[6:7], 0, v[86:87]
	s_waitcnt vmcnt(36)
	v_pk_add_f32 v[78:79], v[78:79], v[218:219]
	v_pk_add_f32 v[76:77], v[76:77], v[216:217]
	v_cvt_pk_bf16_f32 v83, v78, v79
	v_cvt_pk_bf16_f32 v82, v76, v77
	global_store_dwordx4 v[88:89], v[76:79], off
	global_store_dwordx2 v[90:91], v[82:83], off
	v_or_b32_e32 v90, 8, v86
	v_mov_b32_e32 v91, v87
	v_lshl_add_u64 v[90:91], s[6:7], 0, v[90:91]
	v_mul_f32_e32 v77, v77, v77
	v_mul_f32_e32 v79, v79, v79
	v_fmac_f32_e32 v77, v76, v76
	v_fmac_f32_e32 v79, v78, v78
	v_add_f32_e32 v76, v77, v79
	v_pk_add_f32 v[74:75], v[74:75], v[222:223]
	v_pk_add_f32 v[72:73], v[72:73], v[220:221]
	v_cvt_pk_bf16_f32 v83, v74, v75
	v_cvt_pk_bf16_f32 v82, v72, v73
	global_store_dwordx4 v[88:89], v[72:75], off offset:16
	global_store_dwordx2 v[90:91], v[82:83], off
	v_or_b32_e32 v90, 0x100, v86
	v_mov_b32_e32 v91, v87
	v_lshl_add_u64 v[90:91], s[6:7], 0, v[90:91]
	v_mul_f32_e32 v73, v73, v73
	v_mul_f32_e32 v75, v75, v75
	v_fmac_f32_e32 v73, v72, v72
	v_fmac_f32_e32 v75, v74, v74
	v_add_f32_e32 v72, v73, v75
	v_add_f32_e32 v72, v76, v72
	v_or_b32_e32 v86, 0x108, v86
	v_lshl_add_u64 v[86:87], s[6:7], 0, v[86:87]
	v_pk_add_f32 v[70:71], v[70:71], v[226:227]
	v_pk_add_f32 v[68:69], v[68:69], v[224:225]
	v_cvt_pk_bf16_f32 v83, v70, v71
	v_cvt_pk_bf16_f32 v82, v68, v69
	global_store_dwordx4 v[88:89], v[68:71], off offset:512
	global_store_dwordx2 v[90:91], v[82:83], off
	v_mul_f32_e32 v69, v69, v69
	v_mul_f32_e32 v71, v71, v71
	v_fmac_f32_e32 v69, v68, v68
	v_fmac_f32_e32 v71, v70, v70
	v_add_f32_e32 v68, v69, v71
	v_add_f32_e32 v70, v72, v68
	v_pk_add_f32 v[66:67], v[66:67], v[236:237]
	v_pk_add_f32 v[64:65], v[64:65], v[234:235]
	v_mov_b32_e32 v230, 0x160000
	v_lshl_add_u64 v[228:229], v[232:233], 0, v[230:231]
	global_load_dwordx4 v[216:219], v[228:229], off
	global_load_dwordx4 v[220:223], v[228:229], off offset:16
	global_load_dwordx4 v[224:227], v[228:229], off offset:512
	global_load_dwordx4 v[234:237], v[228:229], off offset:528
	global_store_dwordx4 v[88:89], v[64:67], off offset:528
	v_cvt_pk_bf16_f32 v68, v64, v65
	v_cvt_pk_bf16_f32 v69, v66, v67
	v_mul_f32_e32 v65, v65, v65
	v_mul_f32_e32 v67, v67, v67
	v_fmac_f32_e32 v65, v64, v64
	v_fmac_f32_e32 v67, v66, v66
	v_add_f32_e32 v64, v65, v67
	v_add_f32_e32 v64, v70, v64
	v_mov_b32_e32 v65, v64
	s_nop 1
	v_permlane16_swap_b32 v64, v65
	global_store_dwordx2 v[86:87], v[68:69], off
	v_add_f32_e32 v64, v64, v65
	v_mov_b32_e32 v65, v64
	s_nop 1
	v_permlane32_swap_b32 v64, v65
	s_and_saveexec_b64 s[12:13], s[2:3]
	s_cbranch_execz .LBB0_1216
	v_lshl_add_u64 v[66:67], v[80:81], 2, s[8:9]
	v_add_f32_e32 v64, v64, v65
	global_atomic_add_f32 v[66:67], v64, off
.LBB0_1216:
	s_or_b64 exec, exec, s[12:13]
	v_add_u32_e32 v64, 0x80, v148
	v_ashrrev_i32_e32 v65, 31, v64
	v_lshlrev_b64 v[66:67], 11, v[64:65]
	v_lshl_add_u64 v[70:71], v[66:67], 0, v[146:147]
	v_lshl_add_u64 v[72:73], v[70:71], 2, s[30:31]
	v_lshlrev_b64 v[70:71], 1, v[70:71]
	v_lshl_add_u64 v[74:75], s[6:7], 0, v[70:71]
	s_waitcnt vmcnt(38)
	v_pk_add_f32 v[62:63], v[62:63], v[166:167]
	v_pk_add_f32 v[60:61], v[60:61], v[164:165]
	v_cvt_pk_bf16_f32 v67, v62, v63
	v_cvt_pk_bf16_f32 v66, v60, v61
	global_store_dwordx4 v[72:73], v[60:63], off
	global_store_dwordx2 v[74:75], v[66:67], off
	v_or_b32_e32 v74, 8, v70
	v_mov_b32_e32 v75, v71
	v_lshl_add_u64 v[74:75], s[6:7], 0, v[74:75]
	v_mul_f32_e32 v61, v61, v61
	v_mul_f32_e32 v63, v63, v63
	v_fmac_f32_e32 v61, v60, v60
	v_fmac_f32_e32 v63, v62, v62
	v_add_f32_e32 v60, v61, v63
	v_pk_add_f32 v[58:59], v[58:59], v[170:171]
	v_pk_add_f32 v[56:57], v[56:57], v[168:169]
	v_cvt_pk_bf16_f32 v67, v58, v59
	v_cvt_pk_bf16_f32 v66, v56, v57
	global_store_dwordx4 v[72:73], v[56:59], off offset:16
	global_store_dwordx2 v[74:75], v[66:67], off
	v_or_b32_e32 v74, 0x100, v70
	v_mov_b32_e32 v75, v71
	v_lshl_add_u64 v[74:75], s[6:7], 0, v[74:75]
	v_mul_f32_e32 v57, v57, v57
	v_mul_f32_e32 v59, v59, v59
	v_fmac_f32_e32 v57, v56, v56
	v_fmac_f32_e32 v59, v58, v58
	v_add_f32_e32 v56, v57, v59
	v_add_f32_e32 v56, v60, v56
	v_or_b32_e32 v70, 0x108, v70
	v_lshl_add_u64 v[70:71], s[6:7], 0, v[70:71]
	v_pk_add_f32 v[54:55], v[54:55], v[174:175]
	v_pk_add_f32 v[52:53], v[52:53], v[172:173]
	v_cvt_pk_bf16_f32 v67, v54, v55
	v_cvt_pk_bf16_f32 v66, v52, v53
	global_store_dwordx4 v[72:73], v[52:55], off offset:512
	global_store_dwordx2 v[74:75], v[66:67], off
	v_mul_f32_e32 v53, v53, v53
	v_mul_f32_e32 v55, v55, v55
	v_fmac_f32_e32 v53, v52, v52
	v_fmac_f32_e32 v55, v54, v54
	v_add_f32_e32 v52, v53, v55
	v_add_f32_e32 v54, v56, v52
	v_pk_add_f32 v[50:51], v[50:51], v[178:179]
	v_pk_add_f32 v[48:49], v[48:49], v[176:177]
	global_store_dwordx4 v[72:73], v[48:51], off offset:528
	v_cvt_pk_bf16_f32 v52, v48, v49
	v_cvt_pk_bf16_f32 v53, v50, v51
	v_mul_f32_e32 v49, v49, v49
	v_mul_f32_e32 v51, v51, v51
	v_fmac_f32_e32 v49, v48, v48
	v_fmac_f32_e32 v51, v50, v50
	v_add_f32_e32 v48, v49, v51
	v_add_f32_e32 v48, v54, v48
	v_mov_b32_e32 v49, v48
	s_nop 1
	v_permlane16_swap_b32 v48, v49
	global_store_dwordx2 v[70:71], v[52:53], off
	v_add_f32_e32 v48, v48, v49
	v_mov_b32_e32 v49, v48
	s_nop 1
	v_permlane32_swap_b32 v48, v49
	s_and_saveexec_b64 s[12:13], s[2:3]
	s_cbranch_execz .LBB0_1218
	v_lshl_add_u64 v[50:51], v[64:65], 2, s[8:9]
	v_add_f32_e32 v48, v48, v49
	global_atomic_add_f32 v[50:51], v48, off
; __device__ __forceinline__ unsigned pk2(float lo, float hi) { f32x2_t v = {lo, hi}; bf16x2_t b = __builtin_convertvector(v, bf16x2_t); return __builtin_bit_cast(unsigned, b); }
; __device__ __forceinline__ float xor16_sum(float v) { float a = v, b = v; swap16(a, b); return a + b; }
; __device__ __forceinline__ float xor32_sum(float v) { float a = v, b = v; swap32(a, b); return a + b; }
;     __device__ __forceinline__ void operator()(const f32x4 (&acc)[2][2][4][2], const Unit& u, int wr, int wc, int fr, int fq) const {
;     ...
;                 const int row = row0 + ai * HALF + m * 16; float sq = 0.f;
; #pragma unroll
;                 for (int bj = 0; bj < 2; ++bj)
; #pragma unroll
;                     for (int n = 0; n < 2; ++n) {
;                         const size_t idx = (size_t)row * ldc + u.pn * BM + bj * HALF + wc * 32 + 8 * fq + 4 * n;
;                         const f32x4 b = *(const f32x4*)(base + idx);
;                         const f32x4 v = b + acc[ai][bj][m][n] * alpha;
;                         *(f32x4*)(out + idx) = v;
;                         if (NORM) { u32x2 w; w.x = pk2(v[0], v[1]); w.y = pk2(v[2], v[3]); *(u32x2*)(xb + idx) = w; sq += (v[0] * v[0] + v[1] * v[1]) + (v[2] * v[2] + v[3] * v[3]); }
;                     }
;                 if (NORM) { sq = xor16_sum(sq); sq = xor32_sum(sq); if (fq == 0) __hip_atomic_fetch_add(ss + row, sq, __ATOMIC_RELAXED, __HIP_MEMORY_SCOPE_AGENT); }
.LBB0_1218:
	s_or_b64 exec, exec, s[12:13]
	v_add_u32_e32 v48, 0x90, v148
	v_ashrrev_i32_e32 v49, 31, v48
	v_lshlrev_b64 v[50:51], 11, v[48:49]
	v_lshl_add_u64 v[54:55], v[50:51], 0, v[146:147]
	v_lshl_add_u64 v[56:57], v[54:55], 2, s[30:31]
	v_lshlrev_b64 v[54:55], 1, v[54:55]
	v_lshl_add_u64 v[58:59], s[6:7], 0, v[54:55]
	s_waitcnt vmcnt(34)
	v_pk_add_f32 v[46:47], v[46:47], v[182:183]
	v_pk_add_f32 v[44:45], v[44:45], v[180:181]
	v_cvt_pk_bf16_f32 v51, v46, v47
	v_cvt_pk_bf16_f32 v50, v44, v45
	global_store_dwordx4 v[56:57], v[44:47], off
	global_store_dwordx2 v[58:59], v[50:51], off
	v_or_b32_e32 v58, 8, v54
	v_mov_b32_e32 v59, v55
	v_lshl_add_u64 v[58:59], s[6:7], 0, v[58:59]
	v_mul_f32_e32 v45, v45, v45
	v_mul_f32_e32 v47, v47, v47
	v_fmac_f32_e32 v45, v44, v44
	v_fmac_f32_e32 v47, v46, v46
	v_add_f32_e32 v44, v45, v47
	v_pk_add_f32 v[42:43], v[42:43], v[190:191]
	v_pk_add_f32 v[40:41], v[40:41], v[188:189]
	v_cvt_pk_bf16_f32 v51, v42, v43
	v_cvt_pk_bf16_f32 v50, v40, v41
	global_store_dwordx4 v[56:57], v[40:43], off offset:16
	global_store_dwordx2 v[58:59], v[50:51], off
	v_or_b32_e32 v58, 0x100, v54
	v_mov_b32_e32 v59, v55
	v_lshl_add_u64 v[58:59], s[6:7], 0, v[58:59]
	v_mul_f32_e32 v41, v41, v41
	v_mul_f32_e32 v43, v43, v43
	v_fmac_f32_e32 v41, v40, v40
	v_fmac_f32_e32 v43, v42, v42
	v_add_f32_e32 v40, v41, v43
	v_add_f32_e32 v40, v44, v40
	v_or_b32_e32 v54, 0x108, v54
	v_lshl_add_u64 v[54:55], s[6:7], 0, v[54:55]
	v_pk_add_f32 v[38:39], v[38:39], v[194:195]
	v_pk_add_f32 v[36:37], v[36:37], v[192:193]
	v_cvt_pk_bf16_f32 v51, v38, v39
	v_cvt_pk_bf16_f32 v50, v36, v37
	global_store_dwordx4 v[56:57], v[36:39], off offset:512
	global_store_dwordx2 v[58:59], v[50:51], off
	v_mul_f32_e32 v37, v37, v37
	v_mul_f32_e32 v39, v39, v39
	v_fmac_f32_e32 v37, v36, v36
	v_fmac_f32_e32 v39, v38, v38
	v_add_f32_e32 v36, v37, v39
	v_add_f32_e32 v38, v40, v36
	v_pk_add_f32 v[34:35], v[34:35], v[198:199]
	v_pk_add_f32 v[32:33], v[32:33], v[196:197]
	global_store_dwordx4 v[56:57], v[32:35], off offset:528
	v_cvt_pk_bf16_f32 v36, v32, v33
	v_cvt_pk_bf16_f32 v37, v34, v35
	v_mul_f32_e32 v33, v33, v33
	v_mul_f32_e32 v35, v35, v35
	v_fmac_f32_e32 v33, v32, v32
	v_fmac_f32_e32 v35, v34, v34
	v_add_f32_e32 v32, v33, v35
	v_add_f32_e32 v32, v38, v32
	v_mov_b32_e32 v33, v32
	s_nop 1
	v_permlane16_swap_b32 v32, v33
	global_store_dwordx2 v[54:55], v[36:37], off
	v_add_f32_e32 v32, v32, v33
	v_mov_b32_e32 v33, v32
	s_nop 1
	v_permlane32_swap_b32 v32, v33
	s_and_saveexec_b64 s[12:13], s[2:3]
	s_cbranch_execz .LBB0_1220
	v_lshl_add_u64 v[34:35], v[48:49], 2, s[8:9]
	v_add_f32_e32 v32, v32, v33
	global_atomic_add_f32 v[34:35], v32, off
; __device__ __forceinline__ unsigned pk2(float lo, float hi) { f32x2_t v = {lo, hi}; bf16x2_t b = __builtin_convertvector(v, bf16x2_t); return __builtin_bit_cast(unsigned, b); }
; __device__ __forceinline__ float xor16_sum(float v) { float a = v, b = v; swap16(a, b); return a + b; }
; __device__ __forceinline__ float xor32_sum(float v) { float a = v, b = v; swap32(a, b); return a + b; }
;     __device__ __forceinline__ void operator()(const f32x4 (&acc)[2][2][4][2], const Unit& u, int wr, int wc, int fr, int fq) const {
;     ...
;                 const int row = row0 + ai * HALF + m * 16; float sq = 0.f;
; #pragma unroll
;                 for (int bj = 0; bj < 2; ++bj)
; #pragma unroll
;                     for (int n = 0; n < 2; ++n) {
;                         const size_t idx = (size_t)row * ldc + u.pn * BM + bj * HALF + wc * 32 + 8 * fq + 4 * n;
;                         const f32x4 b = *(const f32x4*)(base + idx);
;                         const f32x4 v = b + acc[ai][bj][m][n] * alpha;
;                         *(f32x4*)(out + idx) = v;
;                         if (NORM) { u32x2 w; w.x = pk2(v[0], v[1]); w.y = pk2(v[2], v[3]); *(u32x2*)(xb + idx) = w; sq += (v[0] * v[0] + v[1] * v[1]) + (v[2] * v[2] + v[3] * v[3]); }
;                     }
;                 if (NORM) { sq = xor16_sum(sq); sq = xor32_sum(sq); if (fq == 0) __hip_atomic_fetch_add(ss + row, sq, __ATOMIC_RELAXED, __HIP_MEMORY_SCOPE_AGENT); }
.LBB0_1220:
	s_or_b64 exec, exec, s[12:13]
	v_add_u32_e32 v32, 0xa0, v148
	v_ashrrev_i32_e32 v33, 31, v32
	v_lshlrev_b64 v[34:35], 11, v[32:33]
	v_lshl_add_u64 v[38:39], v[34:35], 0, v[146:147]
	v_lshl_add_u64 v[40:41], v[38:39], 2, s[30:31]
	v_lshlrev_b64 v[38:39], 1, v[38:39]
	v_lshl_add_u64 v[42:43], s[6:7], 0, v[38:39]
	s_waitcnt vmcnt(30)
	v_pk_add_f32 v[30:31], v[30:31], v[202:203]
	v_pk_add_f32 v[28:29], v[28:29], v[200:201]
	v_cvt_pk_bf16_f32 v35, v30, v31
	v_cvt_pk_bf16_f32 v34, v28, v29
	global_store_dwordx4 v[40:41], v[28:31], off
	global_store_dwordx2 v[42:43], v[34:35], off
	v_or_b32_e32 v42, 8, v38
	v_mov_b32_e32 v43, v39
	v_lshl_add_u64 v[42:43], s[6:7], 0, v[42:43]
	v_mul_f32_e32 v29, v29, v29
	v_mul_f32_e32 v31, v31, v31
	v_fmac_f32_e32 v29, v28, v28
	v_fmac_f32_e32 v31, v30, v30
	v_add_f32_e32 v28, v29, v31
	v_pk_add_f32 v[26:27], v[26:27], v[206:207]
	v_pk_add_f32 v[24:25], v[24:25], v[204:205]
	v_cvt_pk_bf16_f32 v35, v26, v27
	v_cvt_pk_bf16_f32 v34, v24, v25
	global_store_dwordx4 v[40:41], v[24:27], off offset:16
	global_store_dwordx2 v[42:43], v[34:35], off
	v_or_b32_e32 v42, 0x100, v38
	v_mov_b32_e32 v43, v39
	v_lshl_add_u64 v[42:43], s[6:7], 0, v[42:43]
	v_mul_f32_e32 v25, v25, v25
	v_mul_f32_e32 v27, v27, v27
	v_fmac_f32_e32 v25, v24, v24
	v_fmac_f32_e32 v27, v26, v26
	v_add_f32_e32 v24, v25, v27
	v_add_f32_e32 v24, v28, v24
	v_or_b32_e32 v38, 0x108, v38
	v_lshl_add_u64 v[38:39], s[6:7], 0, v[38:39]
	v_pk_add_f32 v[22:23], v[22:23], v[210:211]
	v_pk_add_f32 v[20:21], v[20:21], v[208:209]
	v_cvt_pk_bf16_f32 v35, v22, v23
	v_cvt_pk_bf16_f32 v34, v20, v21
	global_store_dwordx4 v[40:41], v[20:23], off offset:512
	global_store_dwordx2 v[42:43], v[34:35], off
	v_mul_f32_e32 v21, v21, v21
	v_mul_f32_e32 v23, v23, v23
	v_fmac_f32_e32 v21, v20, v20
	v_fmac_f32_e32 v23, v22, v22
	v_add_f32_e32 v20, v21, v23
	v_add_f32_e32 v22, v24, v20
	v_pk_add_f32 v[18:19], v[18:19], v[214:215]
	v_pk_add_f32 v[16:17], v[16:17], v[212:213]
	global_store_dwordx4 v[40:41], v[16:19], off offset:528
	v_cvt_pk_bf16_f32 v20, v16, v17
	v_cvt_pk_bf16_f32 v21, v18, v19
	v_mul_f32_e32 v17, v17, v17
	v_mul_f32_e32 v19, v19, v19
	v_fmac_f32_e32 v17, v16, v16
	v_fmac_f32_e32 v19, v18, v18
	v_add_f32_e32 v16, v17, v19
	v_add_f32_e32 v16, v22, v16
	v_mov_b32_e32 v17, v16
	s_nop 1
	v_permlane16_swap_b32 v16, v17
	global_store_dwordx2 v[38:39], v[20:21], off
	v_add_f32_e32 v16, v16, v17
	v_mov_b32_e32 v17, v16
	s_nop 1
	v_permlane32_swap_b32 v16, v17
	s_and_saveexec_b64 s[12:13], s[2:3]
	s_cbranch_execz .LBB0_1222
	v_lshl_add_u64 v[18:19], v[32:33], 2, s[8:9]
	v_add_f32_e32 v16, v16, v17
	global_atomic_add_f32 v[18:19], v16, off
.LBB0_1222:
	s_or_b64 exec, exec, s[12:13]
	v_add_u32_e32 v16, 0xb0, v148
	v_ashrrev_i32_e32 v17, 31, v16
	v_lshlrev_b64 v[18:19], 11, v[16:17]
	v_lshl_add_u64 v[22:23], v[18:19], 0, v[146:147]
	v_lshl_add_u64 v[24:25], v[22:23], 2, s[30:31]
	v_lshlrev_b64 v[22:23], 1, v[22:23]
	v_lshl_add_u64 v[26:27], s[6:7], 0, v[22:23]
	s_waitcnt vmcnt(26)
	v_pk_add_f32 v[14:15], v[14:15], v[218:219]
	v_pk_add_f32 v[12:13], v[12:13], v[216:217]
	v_cvt_pk_bf16_f32 v19, v14, v15
	v_cvt_pk_bf16_f32 v18, v12, v13
	global_store_dwordx4 v[24:25], v[12:15], off
	global_store_dwordx2 v[26:27], v[18:19], off
	v_or_b32_e32 v26, 8, v22
	v_mov_b32_e32 v27, v23
	v_lshl_add_u64 v[26:27], s[6:7], 0, v[26:27]
	v_mul_f32_e32 v13, v13, v13
	v_mul_f32_e32 v15, v15, v15
	v_fmac_f32_e32 v13, v12, v12
	v_fmac_f32_e32 v15, v14, v14
	v_add_f32_e32 v12, v13, v15
	v_pk_add_f32 v[10:11], v[10:11], v[222:223]
	v_pk_add_f32 v[8:9], v[8:9], v[220:221]
	v_cvt_pk_bf16_f32 v19, v10, v11
	v_cvt_pk_bf16_f32 v18, v8, v9
	global_store_dwordx4 v[24:25], v[8:11], off offset:16
	global_store_dwordx2 v[26:27], v[18:19], off
	v_or_b32_e32 v26, 0x100, v22
	v_mov_b32_e32 v27, v23
	v_lshl_add_u64 v[26:27], s[6:7], 0, v[26:27]
	v_mul_f32_e32 v9, v9, v9
	v_mul_f32_e32 v11, v11, v11
	v_fmac_f32_e32 v9, v8, v8
	v_fmac_f32_e32 v11, v10, v10
	v_add_f32_e32 v8, v9, v11
	v_add_f32_e32 v8, v12, v8
	v_or_b32_e32 v22, 0x108, v22
	v_lshl_add_u64 v[22:23], s[6:7], 0, v[22:23]
	v_pk_add_f32 v[6:7], v[6:7], v[226:227]
	v_pk_add_f32 v[4:5], v[4:5], v[224:225]
	v_cvt_pk_bf16_f32 v19, v6, v7
	v_cvt_pk_bf16_f32 v18, v4, v5
	global_store_dwordx4 v[24:25], v[4:7], off offset:512
	global_store_dwordx2 v[26:27], v[18:19], off
	v_mul_f32_e32 v5, v5, v5
	v_mul_f32_e32 v7, v7, v7
	v_fmac_f32_e32 v5, v4, v4
	v_fmac_f32_e32 v7, v6, v6
	v_add_f32_e32 v4, v5, v7
	v_add_f32_e32 v6, v8, v4
	v_pk_add_f32 v[2:3], v[2:3], v[236:237]
	v_pk_add_f32 v[0:1], v[0:1], v[234:235]
	global_store_dwordx4 v[24:25], v[0:3], off offset:528
	v_cvt_pk_bf16_f32 v4, v0, v1
	v_cvt_pk_bf16_f32 v5, v2, v3
	v_mul_f32_e32 v1, v1, v1
	v_mul_f32_e32 v3, v3, v3
	v_fmac_f32_e32 v1, v0, v0
	v_fmac_f32_e32 v3, v2, v2
	v_add_f32_e32 v0, v1, v3
	v_add_f32_e32 v0, v6, v0
	v_mov_b32_e32 v1, v0
	s_nop 1
	v_permlane16_swap_b32 v0, v1
	global_store_dwordx2 v[22:23], v[4:5], off
	v_add_f32_e32 v0, v0, v1
	v_mov_b32_e32 v1, v0
	s_nop 1
	v_permlane32_swap_b32 v0, v1
	s_and_saveexec_b64 s[12:13], s[2:3]
	s_cbranch_execz .LBB0_1224
	v_lshl_add_u64 v[2:3], v[16:17], 2, s[8:9]
	v_add_f32_e32 v0, v0, v1
	global_atomic_add_f32 v[2:3], v0, off

; __device__ __forceinline__ unsigned pk2(float lo, float hi) { f32x2_t v = {lo, hi}; bf16x2_t b = __builtin_convertvector(v, bf16x2_t); return __builtin_bit_cast(unsigned, b); }
; __device__ __forceinline__ float xor16_sum(float v) { float a = v, b = v; swap16(a, b); return a + b; }
; __device__ __forceinline__ float xor32_sum(float v) { float a = v, b = v; swap32(a, b); return a + b; }
;     __device__ __forceinline__ void operator()(const f32x4 (&acc)[2][2][4][2], const Unit& u, int wr, int wc, int fr, int fq) const {
;         const int row0 = u.pm * BM + wr * 64 + fr; constexpr int ldc = 2048; constexpr float alpha = 0.5f * ALPHA2;
;         bf16_t* const xb = (bf16_t*)(ws + XBOFF); __attribute__((address_space(1))) float* const ss = (__attribute__((address_space(1))) float*)(ws + SSOFF);
; #pragma unroll
;         for (int ai = 0; ai < 2; ++ai)
; #pragma unroll
;             for (int m = 0; m < 4; ++m) {
;                 const int row = row0 + ai * HALF + m * 16; float sq = 0.f;
; #pragma unroll
;                 for (int bj = 0; bj < 2; ++bj)
; #pragma unroll
;                     for (int n = 0; n < 2; ++n) {
;                         const size_t idx = (size_t)row * ldc + u.pn * BM + bj * HALF + wc * 32 + 8 * fq + 4 * n;
;                         const f32x4 b = *(const f32x4*)(base + idx);
;                         const f32x4 v = b + acc[ai][bj][m][n] * alpha;
;                         *(f32x4*)(out + idx) = v;
;                         if (NORM) { u32x2 w; w.x = pk2(v[0], v[1]); w.y = pk2(v[2], v[3]); *(u32x2*)(xb + idx) = w; sq += (v[0] * v[0] + v[1] * v[1]) + (v[2] * v[2] + v[3] * v[3]); }
;                     }
;                 if (NORM) { sq = xor16_sum(sq); sq = xor32_sum(sq); if (fq == 0) __hip_atomic_fetch_add(ss + row, sq, __ATOMIC_RELAXED, __HIP_MEMORY_SCOPE_AGENT); }
.LBB0_1605:
	v_lshl_add_u32 v148, s12, 8, v137
	s_lshl_b32 s12, s28, 8
	s_ashr_i32 s13, s12, 31
	v_ashrrev_i32_e32 v149, 31, v148
	v_mov_b32_e32 v147, s13
	v_or_b32_e32 v146, s12, v136
	v_lshlrev_b64 v[154:155], 11, v[148:149]
	v_lshl_add_u64 v[158:159], v[154:155], 0, v[146:147]
	v_lshl_add_u64 v[160:161], v[158:159], 2, s[30:31]
	v_mov_b32_e32 v232, v160
	v_mov_b32_e32 v233, v161
	v_mov_b32_e32 v231, 0
	v_mov_b32_e32 v230, 0x0
	v_lshl_add_u64 v[228:229], v[232:233], 0, v[230:231]
	global_load_dwordx4 v[164:167], v[228:229], off
	global_load_dwordx4 v[168:171], v[228:229], off offset:16
	global_load_dwordx4 v[172:175], v[228:229], off offset:512
	global_load_dwordx4 v[176:179], v[228:229], off offset:528
	v_mov_b32_e32 v230, 0x20000
	v_lshl_add_u64 v[228:229], v[232:233], 0, v[230:231]
	global_load_dwordx4 v[180:183], v[228:229], off
	global_load_dwordx4 v[188:191], v[228:229], off offset:16
	global_load_dwordx4 v[192:195], v[228:229], off offset:512
	global_load_dwordx4 v[196:199], v[228:229], off offset:528
	v_mov_b32_e32 v230, 0x40000
	v_lshl_add_u64 v[228:229], v[232:233], 0, v[230:231]
	global_load_dwordx4 v[200:203], v[228:229], off
	global_load_dwordx4 v[204:207], v[228:229], off offset:16
	global_load_dwordx4 v[208:211], v[228:229], off offset:512
	global_load_dwordx4 v[212:215], v[228:229], off offset:528
	v_mov_b32_e32 v230, 0x60000
	v_lshl_add_u64 v[228:229], v[232:233], 0, v[230:231]
	global_load_dwordx4 v[216:219], v[228:229], off
	global_load_dwordx4 v[220:223], v[228:229], off offset:16
	global_load_dwordx4 v[224:227], v[228:229], off offset:512
	global_load_dwordx4 v[234:237], v[228:229], off offset:528
	v_lshlrev_b64 v[158:159], 1, v[158:159]
	v_lshl_add_u64 v[162:163], s[40:41], 0, v[158:159]
	s_waitcnt vmcnt(12)
	v_pk_add_f32 v[126:127], v[126:127], v[166:167]
	v_pk_add_f32 v[124:125], v[124:125], v[164:165]
	v_cvt_pk_bf16_f32 v155, v126, v127
	v_cvt_pk_bf16_f32 v154, v124, v125
	global_store_dwordx4 v[160:161], v[124:127], off
	global_store_dwordx2 v[162:163], v[154:155], off
	v_or_b32_e32 v162, 8, v158
	v_mov_b32_e32 v163, v159
	v_lshl_add_u64 v[162:163], s[40:41], 0, v[162:163]
	v_mul_f32_e32 v125, v125, v125
	v_mul_f32_e32 v127, v127, v127
	v_fmac_f32_e32 v125, v124, v124
	v_fmac_f32_e32 v127, v126, v126
	v_add_f32_e32 v124, v125, v127
	v_pk_add_f32 v[122:123], v[122:123], v[170:171]
	v_pk_add_f32 v[120:121], v[120:121], v[168:169]
	v_cvt_pk_bf16_f32 v155, v122, v123
	v_cvt_pk_bf16_f32 v154, v120, v121
	global_store_dwordx4 v[160:161], v[120:123], off offset:16
	global_store_dwordx2 v[162:163], v[154:155], off
	v_or_b32_e32 v162, 0x100, v158
	v_mov_b32_e32 v163, v159
	v_lshl_add_u64 v[162:163], s[40:41], 0, v[162:163]
	v_mul_f32_e32 v121, v121, v121
	v_mul_f32_e32 v123, v123, v123
	v_fmac_f32_e32 v121, v120, v120
	v_fmac_f32_e32 v123, v122, v122
	v_add_f32_e32 v120, v121, v123
	v_add_f32_e32 v120, v124, v120
	v_or_b32_e32 v158, 0x108, v158
	v_lshl_add_u64 v[158:159], s[40:41], 0, v[158:159]
	v_pk_add_f32 v[118:119], v[118:119], v[174:175]
	v_pk_add_f32 v[116:117], v[116:117], v[172:173]
	v_cvt_pk_bf16_f32 v155, v118, v119
	v_cvt_pk_bf16_f32 v154, v116, v117
	global_store_dwordx4 v[160:161], v[116:119], off offset:512
	global_store_dwordx2 v[162:163], v[154:155], off
	v_mul_f32_e32 v117, v117, v117
	v_mul_f32_e32 v119, v119, v119
	v_fmac_f32_e32 v117, v116, v116
	v_fmac_f32_e32 v119, v118, v118
	v_add_f32_e32 v116, v117, v119
	v_add_f32_e32 v118, v120, v116
	v_pk_add_f32 v[114:115], v[114:115], v[178:179]
	v_pk_add_f32 v[112:113], v[112:113], v[176:177]
	v_mov_b32_e32 v230, 0x100000
	v_lshl_add_u64 v[228:229], v[232:233], 0, v[230:231]
	global_load_dwordx4 v[164:167], v[228:229], off
	global_load_dwordx4 v[168:171], v[228:229], off offset:16
	global_load_dwordx4 v[172:175], v[228:229], off offset:512
	global_load_dwordx4 v[176:179], v[228:229], off offset:528
	global_store_dwordx4 v[160:161], v[112:115], off offset:528
	v_cvt_pk_bf16_f32 v116, v112, v113
	v_cvt_pk_bf16_f32 v117, v114, v115
	v_mul_f32_e32 v113, v113, v113
	v_mul_f32_e32 v115, v115, v115
	v_fmac_f32_e32 v113, v112, v112
	v_fmac_f32_e32 v115, v114, v114
	v_add_f32_e32 v112, v113, v115
	v_add_f32_e32 v112, v118, v112
	v_mov_b32_e32 v113, v112
	s_nop 1
	v_permlane16_swap_b32 v113, v112
	global_store_dwordx2 v[158:159], v[116:117], off
	v_add_f32_e32 v112, v113, v112
	v_mov_b32_e32 v113, v112
	s_nop 1
	v_permlane32_swap_b32 v113, v112
	s_and_saveexec_b64 s[12:13], s[2:3]
	s_cbranch_execz .LBB0_1607
	v_lshl_add_u64 v[114:115], v[148:149], 2, s[6:7]
	v_add_f32_e32 v112, v113, v112
	global_atomic_add_f32 v[114:115], v112, off
; __device__ __forceinline__ unsigned pk2(float lo, float hi) { f32x2_t v = {lo, hi}; bf16x2_t b = __builtin_convertvector(v, bf16x2_t); return __builtin_bit_cast(unsigned, b); }
; __device__ __forceinline__ float xor16_sum(float v) { float a = v, b = v; swap16(a, b); return a + b; }
; __device__ __forceinline__ float xor32_sum(float v) { float a = v, b = v; swap32(a, b); return a + b; }
;     __device__ __forceinline__ void operator()(const f32x4 (&acc)[2][2][4][2], const Unit& u, int wr, int wc, int fr, int fq) const {
;     ...
;                 const int row = row0 + ai * HALF + m * 16; float sq = 0.f;
; #pragma unroll
;                 for (int bj = 0; bj < 2; ++bj)
; #pragma unroll
;                     for (int n = 0; n < 2; ++n) {
;                         const size_t idx = (size_t)row * ldc + u.pn * BM + bj * HALF + wc * 32 + 8 * fq + 4 * n;
;                         const f32x4 b = *(const f32x4*)(base + idx);
;                         const f32x4 v = b + acc[ai][bj][m][n] * alpha;
;                         *(f32x4*)(out + idx) = v;
;                         if (NORM) { u32x2 w; w.x = pk2(v[0], v[1]); w.y = pk2(v[2], v[3]); *(u32x2*)(xb + idx) = w; sq += (v[0] * v[0] + v[1] * v[1]) + (v[2] * v[2] + v[3] * v[3]); }
;                     }
;                 if (NORM) { sq = xor16_sum(sq); sq = xor32_sum(sq); if (fq == 0) __hip_atomic_fetch_add(ss + row, sq, __ATOMIC_RELAXED, __HIP_MEMORY_SCOPE_AGENT); }
.LBB0_1607:
	s_or_b64 exec, exec, s[12:13]
	v_or_b32_e32 v112, 16, v148
	v_ashrrev_i32_e32 v113, 31, v112
	v_lshlrev_b64 v[114:115], 11, v[112:113]
	v_lshl_add_u64 v[118:119], v[114:115], 0, v[146:147]
	v_lshl_add_u64 v[120:121], v[118:119], 2, s[30:31]
	v_lshlrev_b64 v[118:119], 1, v[118:119]
	v_lshl_add_u64 v[122:123], s[40:41], 0, v[118:119]
	s_waitcnt vmcnt(20)
	v_pk_add_f32 v[110:111], v[110:111], v[182:183]
	v_pk_add_f32 v[108:109], v[108:109], v[180:181]
	v_cvt_pk_bf16_f32 v115, v110, v111
	v_cvt_pk_bf16_f32 v114, v108, v109
	global_store_dwordx4 v[120:121], v[108:111], off
	global_store_dwordx2 v[122:123], v[114:115], off
	v_or_b32_e32 v122, 8, v118
	v_mov_b32_e32 v123, v119
	v_lshl_add_u64 v[122:123], s[40:41], 0, v[122:123]
	v_mul_f32_e32 v109, v109, v109
	v_mul_f32_e32 v111, v111, v111
	v_fmac_f32_e32 v109, v108, v108
	v_fmac_f32_e32 v111, v110, v110
	v_add_f32_e32 v108, v109, v111
	v_pk_add_f32 v[106:107], v[106:107], v[190:191]
	v_pk_add_f32 v[104:105], v[104:105], v[188:189]
	v_cvt_pk_bf16_f32 v115, v106, v107
	v_cvt_pk_bf16_f32 v114, v104, v105
	global_store_dwordx4 v[120:121], v[104:107], off offset:16
	global_store_dwordx2 v[122:123], v[114:115], off
	v_or_b32_e32 v122, 0x100, v118
	v_mov_b32_e32 v123, v119
	v_lshl_add_u64 v[122:123], s[40:41], 0, v[122:123]
	v_mul_f32_e32 v105, v105, v105
	v_mul_f32_e32 v107, v107, v107
	v_fmac_f32_e32 v105, v104, v104
	v_fmac_f32_e32 v107, v106, v106
	v_add_f32_e32 v104, v105, v107
	v_add_f32_e32 v104, v108, v104
	v_or_b32_e32 v118, 0x108, v118
	v_lshl_add_u64 v[118:119], s[40:41], 0, v[118:119]
	v_pk_add_f32 v[102:103], v[102:103], v[194:195]
	v_pk_add_f32 v[100:101], v[100:101], v[192:193]
	v_cvt_pk_bf16_f32 v115, v102, v103
	v_cvt_pk_bf16_f32 v114, v100, v101
	global_store_dwordx4 v[120:121], v[100:103], off offset:512
	global_store_dwordx2 v[122:123], v[114:115], off
	v_mul_f32_e32 v101, v101, v101
	v_mul_f32_e32 v103, v103, v103
	v_fmac_f32_e32 v101, v100, v100
	v_fmac_f32_e32 v103, v102, v102
	v_add_f32_e32 v100, v101, v103
	v_add_f32_e32 v102, v104, v100
	v_pk_add_f32 v[98:99], v[98:99], v[198:199]
	v_pk_add_f32 v[96:97], v[96:97], v[196:197]
	v_mov_b32_e32 v230, 0x120000
	v_lshl_add_u64 v[228:229], v[232:233], 0, v[230:231]
	global_load_dwordx4 v[180:183], v[228:229], off
	global_load_dwordx4 v[188:191], v[228:229], off offset:16
	global_load_dwordx4 v[192:195], v[228:229], off offset:512
	global_load_dwordx4 v[196:199], v[228:229], off offset:528
	global_store_dwordx4 v[120:121], v[96:99], off offset:528
	v_cvt_pk_bf16_f32 v100, v96, v97
	v_cvt_pk_bf16_f32 v101, v98, v99
	v_mul_f32_e32 v97, v97, v97
	v_mul_f32_e32 v99, v99, v99
	v_fmac_f32_e32 v97, v96, v96
	v_fmac_f32_e32 v99, v98, v98
	v_add_f32_e32 v96, v97, v99
	v_add_f32_e32 v96, v102, v96
	v_mov_b32_e32 v97, v96
	s_nop 1
	v_permlane16_swap_b32 v96, v97
	global_store_dwordx2 v[118:119], v[100:101], off
	v_add_f32_e32 v96, v96, v97
	v_mov_b32_e32 v97, v96
	s_nop 1
	v_permlane32_swap_b32 v96, v97
	s_and_saveexec_b64 s[12:13], s[2:3]
	s_cbranch_execz .LBB0_1609
	v_lshl_add_u64 v[98:99], v[112:113], 2, s[6:7]
	v_add_f32_e32 v96, v96, v97
	global_atomic_add_f32 v[98:99], v96, off
.LBB0_1609:
	s_or_b64 exec, exec, s[12:13]
	v_or_b32_e32 v96, 32, v148
	v_ashrrev_i32_e32 v97, 31, v96
	v_lshlrev_b64 v[98:99], 11, v[96:97]
	v_lshl_add_u64 v[102:103], v[98:99], 0, v[146:147]
	v_lshl_add_u64 v[104:105], v[102:103], 2, s[30:31]
	v_lshlrev_b64 v[102:103], 1, v[102:103]
	v_lshl_add_u64 v[106:107], s[40:41], 0, v[102:103]
	s_waitcnt vmcnt(28)
	v_pk_add_f32 v[94:95], v[94:95], v[202:203]
	v_pk_add_f32 v[92:93], v[92:93], v[200:201]
	v_cvt_pk_bf16_f32 v99, v94, v95
	v_cvt_pk_bf16_f32 v98, v92, v93
	global_store_dwordx4 v[104:105], v[92:95], off
	global_store_dwordx2 v[106:107], v[98:99], off
	v_or_b32_e32 v106, 8, v102
	v_mov_b32_e32 v107, v103
	v_lshl_add_u64 v[106:107], s[40:41], 0, v[106:107]
	v_mul_f32_e32 v93, v93, v93
	v_mul_f32_e32 v95, v95, v95
	v_fmac_f32_e32 v93, v92, v92
	v_fmac_f32_e32 v95, v94, v94
	v_add_f32_e32 v92, v93, v95
	v_pk_add_f32 v[90:91], v[90:91], v[206:207]
	v_pk_add_f32 v[88:89], v[88:89], v[204:205]
	v_cvt_pk_bf16_f32 v99, v90, v91
	v_cvt_pk_bf16_f32 v98, v88, v89
	global_store_dwordx4 v[104:105], v[88:91], off offset:16
	global_store_dwordx2 v[106:107], v[98:99], off
	v_or_b32_e32 v106, 0x100, v102
	v_mov_b32_e32 v107, v103
	v_lshl_add_u64 v[106:107], s[40:41], 0, v[106:107]
	v_mul_f32_e32 v89, v89, v89
	v_mul_f32_e32 v91, v91, v91
	v_fmac_f32_e32 v89, v88, v88
	v_fmac_f32_e32 v91, v90, v90
	v_add_f32_e32 v88, v89, v91
	v_add_f32_e32 v88, v92, v88
	v_or_b32_e32 v102, 0x108, v102
	v_lshl_add_u64 v[102:103], s[40:41], 0, v[102:103]
	v_pk_add_f32 v[86:87], v[86:87], v[210:211]
	v_pk_add_f32 v[84:85], v[84:85], v[208:209]
	v_cvt_pk_bf16_f32 v99, v86, v87
	v_cvt_pk_bf16_f32 v98, v84, v85
	global_store_dwordx4 v[104:105], v[84:87], off offset:512
	global_store_dwordx2 v[106:107], v[98:99], off
	v_mul_f32_e32 v85, v85, v85
	v_mul_f32_e32 v87, v87, v87
	v_fmac_f32_e32 v85, v84, v84
	v_fmac_f32_e32 v87, v86, v86
	v_add_f32_e32 v84, v85, v87
	v_add_f32_e32 v86, v88, v84
	v_pk_add_f32 v[82:83], v[82:83], v[214:215]
	v_pk_add_f32 v[80:81], v[80:81], v[212:213]
	v_mov_b32_e32 v230, 0x140000
	v_lshl_add_u64 v[228:229], v[232:233], 0, v[230:231]
	global_load_dwordx4 v[200:203], v[228:229], off
	global_load_dwordx4 v[204:207], v[228:229], off offset:16
	global_load_dwordx4 v[208:211], v[228:229], off offset:512
	global_load_dwordx4 v[212:215], v[228:229], off offset:528
	global_store_dwordx4 v[104:105], v[80:83], off offset:528
	v_cvt_pk_bf16_f32 v84, v80, v81
	v_cvt_pk_bf16_f32 v85, v82, v83
	v_mul_f32_e32 v81, v81, v81
	v_mul_f32_e32 v83, v83, v83
	v_fmac_f32_e32 v81, v80, v80
	v_fmac_f32_e32 v83, v82, v82
	v_add_f32_e32 v80, v81, v83
	v_add_f32_e32 v80, v86, v80
	v_mov_b32_e32 v81, v80
	s_nop 1
	v_permlane16_swap_b32 v80, v81
	global_store_dwordx2 v[102:103], v[84:85], off
	v_add_f32_e32 v80, v80, v81
	v_mov_b32_e32 v81, v80
	s_nop 1
	v_permlane32_swap_b32 v80, v81
	s_and_saveexec_b64 s[12:13], s[2:3]
	s_cbranch_execz .LBB0_1611
	v_lshl_add_u64 v[82:83], v[96:97], 2, s[6:7]
	v_add_f32_e32 v80, v80, v81
	global_atomic_add_f32 v[82:83], v80, off
; __device__ __forceinline__ unsigned pk2(float lo, float hi) { f32x2_t v = {lo, hi}; bf16x2_t b = __builtin_convertvector(v, bf16x2_t); return __builtin_bit_cast(unsigned, b); }
; __device__ __forceinline__ float xor16_sum(float v) { float a = v, b = v; swap16(a, b); return a + b; }
; __device__ __forceinline__ float xor32_sum(float v) { float a = v, b = v; swap32(a, b); return a + b; }
;     __device__ __forceinline__ void operator()(const f32x4 (&acc)[2][2][4][2], const Unit& u, int wr, int wc, int fr, int fq) const {
;     ...
;                 const int row = row0 + ai * HALF + m * 16; float sq = 0.f;
; #pragma unroll
;                 for (int bj = 0; bj < 2; ++bj)
; #pragma unroll
;                     for (int n = 0; n < 2; ++n) {
;                         const size_t idx = (size_t)row * ldc + u.pn * BM + bj * HALF + wc * 32 + 8 * fq + 4 * n;
;                         const f32x4 b = *(const f32x4*)(base + idx);
;                         const f32x4 v = b + acc[ai][bj][m][n] * alpha;
;                         *(f32x4*)(out + idx) = v;
;                         if (NORM) { u32x2 w; w.x = pk2(v[0], v[1]); w.y = pk2(v[2], v[3]); *(u32x2*)(xb + idx) = w; sq += (v[0] * v[0] + v[1] * v[1]) + (v[2] * v[2] + v[3] * v[3]); }
;                     }
;                 if (NORM) { sq = xor16_sum(sq); sq = xor32_sum(sq); if (fq == 0) __hip_atomic_fetch_add(ss + row, sq, __ATOMIC_RELAXED, __HIP_MEMORY_SCOPE_AGENT); }
.LBB0_1611:
	s_or_b64 exec, exec, s[12:13]
	v_or_b32_e32 v80, 48, v148
	v_ashrrev_i32_e32 v81, 31, v80
	v_lshlrev_b64 v[82:83], 11, v[80:81]
	v_lshl_add_u64 v[86:87], v[82:83], 0, v[146:147]
	v_lshl_add_u64 v[88:89], v[86:87], 2, s[30:31]
	v_lshlrev_b64 v[86:87], 1, v[86:87]
	v_lshl_add_u64 v[90:91], s[40:41], 0, v[86:87]
	s_waitcnt vmcnt(36)
	v_pk_add_f32 v[78:79], v[78:79], v[218:219]
	v_pk_add_f32 v[76:77], v[76:77], v[216:217]
	v_cvt_pk_bf16_f32 v83, v78, v79
	v_cvt_pk_bf16_f32 v82, v76, v77
	global_store_dwordx4 v[88:89], v[76:79], off
	global_store_dwordx2 v[90:91], v[82:83], off
	v_or_b32_e32 v90, 8, v86
	v_mov_b32_e32 v91, v87
	v_lshl_add_u64 v[90:91], s[40:41], 0, v[90:91]
	v_mul_f32_e32 v77, v77, v77
	v_mul_f32_e32 v79, v79, v79
	v_fmac_f32_e32 v77, v76, v76
	v_fmac_f32_e32 v79, v78, v78
	v_add_f32_e32 v76, v77, v79
	v_pk_add_f32 v[74:75], v[74:75], v[222:223]
	v_pk_add_f32 v[72:73], v[72:73], v[220:221]
	v_cvt_pk_bf16_f32 v83, v74, v75
	v_cvt_pk_bf16_f32 v82, v72, v73
	global_store_dwordx4 v[88:89], v[72:75], off offset:16
	global_store_dwordx2 v[90:91], v[82:83], off
	v_or_b32_e32 v90, 0x100, v86
	v_mov_b32_e32 v91, v87
	v_lshl_add_u64 v[90:91], s[40:41], 0, v[90:91]
	v_mul_f32_e32 v73, v73, v73
	v_mul_f32_e32 v75, v75, v75
	v_fmac_f32_e32 v73, v72, v72
	v_fmac_f32_e32 v75, v74, v74
	v_add_f32_e32 v72, v73, v75
	v_add_f32_e32 v72, v76, v72
	v_or_b32_e32 v86, 0x108, v86
	v_lshl_add_u64 v[86:87], s[40:41], 0, v[86:87]
	v_pk_add_f32 v[70:71], v[70:71], v[226:227]
	v_pk_add_f32 v[68:69], v[68:69], v[224:225]
	v_cvt_pk_bf16_f32 v83, v70, v71
	v_cvt_pk_bf16_f32 v82, v68, v69
	global_store_dwordx4 v[88:89], v[68:71], off offset:512
	global_store_dwordx2 v[90:91], v[82:83], off
	v_mul_f32_e32 v69, v69, v69
	v_mul_f32_e32 v71, v71, v71
	v_fmac_f32_e32 v69, v68, v68
	v_fmac_f32_e32 v71, v70, v70
	v_add_f32_e32 v68, v69, v71
	v_add_f32_e32 v70, v72, v68
	v_pk_add_f32 v[66:67], v[66:67], v[236:237]
	v_pk_add_f32 v[64:65], v[64:65], v[234:235]
	v_mov_b32_e32 v230, 0x160000
	v_lshl_add_u64 v[228:229], v[232:233], 0, v[230:231]
	global_load_dwordx4 v[216:219], v[228:229], off
	global_load_dwordx4 v[220:223], v[228:229], off offset:16
	global_load_dwordx4 v[224:227], v[228:229], off offset:512
	global_load_dwordx4 v[234:237], v[228:229], off offset:528
	global_store_dwordx4 v[88:89], v[64:67], off offset:528
	v_cvt_pk_bf16_f32 v68, v64, v65
	v_cvt_pk_bf16_f32 v69, v66, v67
	v_mul_f32_e32 v65, v65, v65
	v_mul_f32_e32 v67, v67, v67
	v_fmac_f32_e32 v65, v64, v64
	v_fmac_f32_e32 v67, v66, v66
	v_add_f32_e32 v64, v65, v67
	v_add_f32_e32 v64, v70, v64
	v_mov_b32_e32 v65, v64
	s_nop 1
	v_permlane16_swap_b32 v64, v65
	global_store_dwordx2 v[86:87], v[68:69], off
	v_add_f32_e32 v64, v64, v65
	v_mov_b32_e32 v65, v64
	s_nop 1
	v_permlane32_swap_b32 v64, v65
	s_and_saveexec_b64 s[12:13], s[2:3]
	s_cbranch_execz .LBB0_1613
	v_lshl_add_u64 v[66:67], v[80:81], 2, s[6:7]
	v_add_f32_e32 v64, v64, v65
	global_atomic_add_f32 v[66:67], v64, off
.LBB0_1613:
	s_or_b64 exec, exec, s[12:13]
	v_add_u32_e32 v64, 0x80, v148
	v_ashrrev_i32_e32 v65, 31, v64
	v_lshlrev_b64 v[66:67], 11, v[64:65]
	v_lshl_add_u64 v[70:71], v[66:67], 0, v[146:147]
	v_lshl_add_u64 v[72:73], v[70:71], 2, s[30:31]
	v_lshlrev_b64 v[70:71], 1, v[70:71]
	v_lshl_add_u64 v[74:75], s[40:41], 0, v[70:71]
	s_waitcnt vmcnt(38)
	v_pk_add_f32 v[62:63], v[62:63], v[166:167]
	v_pk_add_f32 v[60:61], v[60:61], v[164:165]
	v_cvt_pk_bf16_f32 v67, v62, v63
	v_cvt_pk_bf16_f32 v66, v60, v61
	global_store_dwordx4 v[72:73], v[60:63], off
	global_store_dwordx2 v[74:75], v[66:67], off
	v_or_b32_e32 v74, 8, v70
	v_mov_b32_e32 v75, v71
	v_lshl_add_u64 v[74:75], s[40:41], 0, v[74:75]
	v_mul_f32_e32 v61, v61, v61
	v_mul_f32_e32 v63, v63, v63
	v_fmac_f32_e32 v61, v60, v60
	v_fmac_f32_e32 v63, v62, v62
	v_add_f32_e32 v60, v61, v63
	v_pk_add_f32 v[58:59], v[58:59], v[170:171]
	v_pk_add_f32 v[56:57], v[56:57], v[168:169]
	v_cvt_pk_bf16_f32 v67, v58, v59
	v_cvt_pk_bf16_f32 v66, v56, v57
	global_store_dwordx4 v[72:73], v[56:59], off offset:16
	global_store_dwordx2 v[74:75], v[66:67], off
	v_or_b32_e32 v74, 0x100, v70
	v_mov_b32_e32 v75, v71
	v_lshl_add_u64 v[74:75], s[40:41], 0, v[74:75]
	v_mul_f32_e32 v57, v57, v57
	v_mul_f32_e32 v59, v59, v59
	v_fmac_f32_e32 v57, v56, v56
	v_fmac_f32_e32 v59, v58, v58
	v_add_f32_e32 v56, v57, v59
	v_add_f32_e32 v56, v60, v56
	v_or_b32_e32 v70, 0x108, v70
	v_lshl_add_u64 v[70:71], s[40:41], 0, v[70:71]
	v_pk_add_f32 v[54:55], v[54:55], v[174:175]
	v_pk_add_f32 v[52:53], v[52:53], v[172:173]
	v_cvt_pk_bf16_f32 v67, v54, v55
	v_cvt_pk_bf16_f32 v66, v52, v53
	global_store_dwordx4 v[72:73], v[52:55], off offset:512
	global_store_dwordx2 v[74:75], v[66:67], off
	v_mul_f32_e32 v53, v53, v53
	v_mul_f32_e32 v55, v55, v55
	v_fmac_f32_e32 v53, v52, v52
	v_fmac_f32_e32 v55, v54, v54
	v_add_f32_e32 v52, v53, v55
	v_add_f32_e32 v54, v56, v52
	v_pk_add_f32 v[50:51], v[50:51], v[178:179]
	v_pk_add_f32 v[48:49], v[48:49], v[176:177]
	global_store_dwordx4 v[72:73], v[48:51], off offset:528
	v_cvt_pk_bf16_f32 v52, v48, v49
	v_cvt_pk_bf16_f32 v53, v50, v51
	v_mul_f32_e32 v49, v49, v49
	v_mul_f32_e32 v51, v51, v51
	v_fmac_f32_e32 v49, v48, v48
	v_fmac_f32_e32 v51, v50, v50
	v_add_f32_e32 v48, v49, v51
	v_add_f32_e32 v48, v54, v48
	v_mov_b32_e32 v49, v48
	s_nop 1
	v_permlane16_swap_b32 v48, v49
	global_store_dwordx2 v[70:71], v[52:53], off
	v_add_f32_e32 v48, v48, v49
	v_mov_b32_e32 v49, v48
	s_nop 1
	v_permlane32_swap_b32 v48, v49
	s_and_saveexec_b64 s[12:13], s[2:3]
	s_cbranch_execz .LBB0_1615
	v_lshl_add_u64 v[50:51], v[64:65], 2, s[6:7]
	v_add_f32_e32 v48, v48, v49
	global_atomic_add_f32 v[50:51], v48, off
; __device__ __forceinline__ unsigned pk2(float lo, float hi) { f32x2_t v = {lo, hi}; bf16x2_t b = __builtin_convertvector(v, bf16x2_t); return __builtin_bit_cast(unsigned, b); }
; __device__ __forceinline__ float xor16_sum(float v) { float a = v, b = v; swap16(a, b); return a + b; }
; __device__ __forceinline__ float xor32_sum(float v) { float a = v, b = v; swap32(a, b); return a + b; }
;     __device__ __forceinline__ void operator()(const f32x4 (&acc)[2][2][4][2], const Unit& u, int wr, int wc, int fr, int fq) const {
;     ...
;                 const int row = row0 + ai * HALF + m * 16; float sq = 0.f;
; #pragma unroll
;                 for (int bj = 0; bj < 2; ++bj)
; #pragma unroll
;                     for (int n = 0; n < 2; ++n) {
;                         const size_t idx = (size_t)row * ldc + u.pn * BM + bj * HALF + wc * 32 + 8 * fq + 4 * n;
;                         const f32x4 b = *(const f32x4*)(base + idx);
;                         const f32x4 v = b + acc[ai][bj][m][n] * alpha;
;                         *(f32x4*)(out + idx) = v;
;                         if (NORM) { u32x2 w; w.x = pk2(v[0], v[1]); w.y = pk2(v[2], v[3]); *(u32x2*)(xb + idx) = w; sq += (v[0] * v[0] + v[1] * v[1]) + (v[2] * v[2] + v[3] * v[3]); }
;                     }
;                 if (NORM) { sq = xor16_sum(sq); sq = xor32_sum(sq); if (fq == 0) __hip_atomic_fetch_add(ss + row, sq, __ATOMIC_RELAXED, __HIP_MEMORY_SCOPE_AGENT); }
.LBB0_1615:
	s_or_b64 exec, exec, s[12:13]
	v_add_u32_e32 v48, 0x90, v148
	v_ashrrev_i32_e32 v49, 31, v48
	v_lshlrev_b64 v[50:51], 11, v[48:49]
	v_lshl_add_u64 v[54:55], v[50:51], 0, v[146:147]
	v_lshl_add_u64 v[56:57], v[54:55], 2, s[30:31]
	v_lshlrev_b64 v[54:55], 1, v[54:55]
	v_lshl_add_u64 v[58:59], s[40:41], 0, v[54:55]
	s_waitcnt vmcnt(34)
	v_pk_add_f32 v[46:47], v[46:47], v[182:183]
	v_pk_add_f32 v[44:45], v[44:45], v[180:181]
	v_cvt_pk_bf16_f32 v51, v46, v47
	v_cvt_pk_bf16_f32 v50, v44, v45
	global_store_dwordx4 v[56:57], v[44:47], off
	global_store_dwordx2 v[58:59], v[50:51], off
	v_or_b32_e32 v58, 8, v54
	v_mov_b32_e32 v59, v55
	v_lshl_add_u64 v[58:59], s[40:41], 0, v[58:59]
	v_mul_f32_e32 v45, v45, v45
	v_mul_f32_e32 v47, v47, v47
	v_fmac_f32_e32 v45, v44, v44
	v_fmac_f32_e32 v47, v46, v46
	v_add_f32_e32 v44, v45, v47
	v_pk_add_f32 v[42:43], v[42:43], v[190:191]
	v_pk_add_f32 v[40:41], v[40:41], v[188:189]
	v_cvt_pk_bf16_f32 v51, v42, v43
	v_cvt_pk_bf16_f32 v50, v40, v41
	global_store_dwordx4 v[56:57], v[40:43], off offset:16
	global_store_dwordx2 v[58:59], v[50:51], off
	v_or_b32_e32 v58, 0x100, v54
	v_mov_b32_e32 v59, v55
	v_lshl_add_u64 v[58:59], s[40:41], 0, v[58:59]
	v_mul_f32_e32 v41, v41, v41
	v_mul_f32_e32 v43, v43, v43
	v_fmac_f32_e32 v41, v40, v40
	v_fmac_f32_e32 v43, v42, v42
	v_add_f32_e32 v40, v41, v43
	v_add_f32_e32 v40, v44, v40
	v_or_b32_e32 v54, 0x108, v54
	v_lshl_add_u64 v[54:55], s[40:41], 0, v[54:55]
	v_pk_add_f32 v[38:39], v[38:39], v[194:195]
	v_pk_add_f32 v[36:37], v[36:37], v[192:193]
	v_cvt_pk_bf16_f32 v51, v38, v39
	v_cvt_pk_bf16_f32 v50, v36, v37
	global_store_dwordx4 v[56:57], v[36:39], off offset:512
	global_store_dwordx2 v[58:59], v[50:51], off
	v_mul_f32_e32 v37, v37, v37
	v_mul_f32_e32 v39, v39, v39
	v_fmac_f32_e32 v37, v36, v36
	v_fmac_f32_e32 v39, v38, v38
	v_add_f32_e32 v36, v37, v39
	v_add_f32_e32 v38, v40, v36
	v_pk_add_f32 v[34:35], v[34:35], v[198:199]
	v_pk_add_f32 v[32:33], v[32:33], v[196:197]
	global_store_dwordx4 v[56:57], v[32:35], off offset:528
	v_cvt_pk_bf16_f32 v36, v32, v33
	v_cvt_pk_bf16_f32 v37, v34, v35
	v_mul_f32_e32 v33, v33, v33
	v_mul_f32_e32 v35, v35, v35
	v_fmac_f32_e32 v33, v32, v32
	v_fmac_f32_e32 v35, v34, v34
	v_add_f32_e32 v32, v33, v35
	v_add_f32_e32 v32, v38, v32
	v_mov_b32_e32 v33, v32
	s_nop 1
	v_permlane16_swap_b32 v32, v33
	global_store_dwordx2 v[54:55], v[36:37], off
	v_add_f32_e32 v32, v32, v33
	v_mov_b32_e32 v33, v32
	s_nop 1
	v_permlane32_swap_b32 v32, v33
	s_and_saveexec_b64 s[12:13], s[2:3]
	s_cbranch_execz .LBB0_1617
	v_lshl_add_u64 v[34:35], v[48:49], 2, s[6:7]
	v_add_f32_e32 v32, v32, v33
	global_atomic_add_f32 v[34:35], v32, off
; __device__ __forceinline__ unsigned pk2(float lo, float hi) { f32x2_t v = {lo, hi}; bf16x2_t b = __builtin_convertvector(v, bf16x2_t); return __builtin_bit_cast(unsigned, b); }
; __device__ __forceinline__ float xor16_sum(float v) { float a = v, b = v; swap16(a, b); return a + b; }
; __device__ __forceinline__ float xor32_sum(float v) { float a = v, b = v; swap32(a, b); return a + b; }
;     __device__ __forceinline__ void operator()(const f32x4 (&acc)[2][2][4][2], const Unit& u, int wr, int wc, int fr, int fq) const {
;     ...
;                 const int row = row0 + ai * HALF + m * 16; float sq = 0.f;
; #pragma unroll
;                 for (int bj = 0; bj < 2; ++bj)
; #pragma unroll
;                     for (int n = 0; n < 2; ++n) {
;                         const size_t idx = (size_t)row * ldc + u.pn * BM + bj * HALF + wc * 32 + 8 * fq + 4 * n;
;                         const f32x4 b = *(const f32x4*)(base + idx);
;                         const f32x4 v = b + acc[ai][bj][m][n] * alpha;
;                         *(f32x4*)(out + idx) = v;
;                         if (NORM) { u32x2 w; w.x = pk2(v[0], v[1]); w.y = pk2(v[2], v[3]); *(u32x2*)(xb + idx) = w; sq += (v[0] * v[0] + v[1] * v[1]) + (v[2] * v[2] + v[3] * v[3]); }
;                     }
;                 if (NORM) { sq = xor16_sum(sq); sq = xor32_sum(sq); if (fq == 0) __hip_atomic_fetch_add(ss + row, sq, __ATOMIC_RELAXED, __HIP_MEMORY_SCOPE_AGENT); }
.LBB0_1617:
	s_or_b64 exec, exec, s[12:13]
	v_add_u32_e32 v32, 0xa0, v148
	v_ashrrev_i32_e32 v33, 31, v32
	v_lshlrev_b64 v[34:35], 11, v[32:33]
	v_lshl_add_u64 v[38:39], v[34:35], 0, v[146:147]
	v_lshl_add_u64 v[40:41], v[38:39], 2, s[30:31]
	v_lshlrev_b64 v[38:39], 1, v[38:39]
	v_lshl_add_u64 v[42:43], s[40:41], 0, v[38:39]
	s_waitcnt vmcnt(30)
	v_pk_add_f32 v[30:31], v[30:31], v[202:203]
	v_pk_add_f32 v[28:29], v[28:29], v[200:201]
	v_cvt_pk_bf16_f32 v35, v30, v31
	v_cvt_pk_bf16_f32 v34, v28, v29
	global_store_dwordx4 v[40:41], v[28:31], off
	global_store_dwordx2 v[42:43], v[34:35], off
	v_or_b32_e32 v42, 8, v38
	v_mov_b32_e32 v43, v39
	v_lshl_add_u64 v[42:43], s[40:41], 0, v[42:43]
	v_mul_f32_e32 v29, v29, v29
	v_mul_f32_e32 v31, v31, v31
	v_fmac_f32_e32 v29, v28, v28
	v_fmac_f32_e32 v31, v30, v30
	v_add_f32_e32 v28, v29, v31
	v_pk_add_f32 v[26:27], v[26:27], v[206:207]
	v_pk_add_f32 v[24:25], v[24:25], v[204:205]
	v_cvt_pk_bf16_f32 v35, v26, v27
	v_cvt_pk_bf16_f32 v34, v24, v25
	global_store_dwordx4 v[40:41], v[24:27], off offset:16
	global_store_dwordx2 v[42:43], v[34:35], off
	v_or_b32_e32 v42, 0x100, v38
	v_mov_b32_e32 v43, v39
	v_lshl_add_u64 v[42:43], s[40:41], 0, v[42:43]
	v_mul_f32_e32 v25, v25, v25
	v_mul_f32_e32 v27, v27, v27
	v_fmac_f32_e32 v25, v24, v24
	v_fmac_f32_e32 v27, v26, v26
	v_add_f32_e32 v24, v25, v27
	v_add_f32_e32 v24, v28, v24
	v_or_b32_e32 v38, 0x108, v38
	v_lshl_add_u64 v[38:39], s[40:41], 0, v[38:39]
	v_pk_add_f32 v[22:23], v[22:23], v[210:211]
	v_pk_add_f32 v[20:21], v[20:21], v[208:209]
	v_cvt_pk_bf16_f32 v35, v22, v23
	v_cvt_pk_bf16_f32 v34, v20, v21
	global_store_dwordx4 v[40:41], v[20:23], off offset:512
	global_store_dwordx2 v[42:43], v[34:35], off
	v_mul_f32_e32 v21, v21, v21
	v_mul_f32_e32 v23, v23, v23
	v_fmac_f32_e32 v21, v20, v20
	v_fmac_f32_e32 v23, v22, v22
	v_add_f32_e32 v20, v21, v23
	v_add_f32_e32 v22, v24, v20
	v_pk_add_f32 v[18:19], v[18:19], v[214:215]
	v_pk_add_f32 v[16:17], v[16:17], v[212:213]
	global_store_dwordx4 v[40:41], v[16:19], off offset:528
	v_cvt_pk_bf16_f32 v20, v16, v17
	v_cvt_pk_bf16_f32 v21, v18, v19
	v_mul_f32_e32 v17, v17, v17
	v_mul_f32_e32 v19, v19, v19
	v_fmac_f32_e32 v17, v16, v16
	v_fmac_f32_e32 v19, v18, v18
	v_add_f32_e32 v16, v17, v19
	v_add_f32_e32 v16, v22, v16
	v_mov_b32_e32 v17, v16
	s_nop 1
	v_permlane16_swap_b32 v16, v17
	global_store_dwordx2 v[38:39], v[20:21], off
	v_add_f32_e32 v16, v16, v17
	v_mov_b32_e32 v17, v16
	s_nop 1
	v_permlane32_swap_b32 v16, v17
	s_and_saveexec_b64 s[12:13], s[2:3]
	s_cbranch_execz .LBB0_1619
	v_lshl_add_u64 v[18:19], v[32:33], 2, s[6:7]
	v_add_f32_e32 v16, v16, v17
	global_atomic_add_f32 v[18:19], v16, off
.LBB0_1619:
	s_or_b64 exec, exec, s[12:13]
	v_add_u32_e32 v16, 0xb0, v148
	v_ashrrev_i32_e32 v17, 31, v16
	v_lshlrev_b64 v[18:19], 11, v[16:17]
	v_lshl_add_u64 v[22:23], v[18:19], 0, v[146:147]
	v_lshl_add_u64 v[24:25], v[22:23], 2, s[30:31]
	v_lshlrev_b64 v[22:23], 1, v[22:23]
	v_lshl_add_u64 v[26:27], s[40:41], 0, v[22:23]
	s_waitcnt vmcnt(26)
	v_pk_add_f32 v[14:15], v[14:15], v[218:219]
	v_pk_add_f32 v[12:13], v[12:13], v[216:217]
	v_cvt_pk_bf16_f32 v19, v14, v15
	v_cvt_pk_bf16_f32 v18, v12, v13
	global_store_dwordx4 v[24:25], v[12:15], off
	global_store_dwordx2 v[26:27], v[18:19], off
	v_or_b32_e32 v26, 8, v22
	v_mov_b32_e32 v27, v23
	v_lshl_add_u64 v[26:27], s[40:41], 0, v[26:27]
	v_mul_f32_e32 v13, v13, v13
	v_mul_f32_e32 v15, v15, v15
	v_fmac_f32_e32 v13, v12, v12
	v_fmac_f32_e32 v15, v14, v14
	v_add_f32_e32 v12, v13, v15
	v_pk_add_f32 v[10:11], v[10:11], v[222:223]
	v_pk_add_f32 v[8:9], v[8:9], v[220:221]
	v_cvt_pk_bf16_f32 v19, v10, v11
	v_cvt_pk_bf16_f32 v18, v8, v9
	global_store_dwordx4 v[24:25], v[8:11], off offset:16
	global_store_dwordx2 v[26:27], v[18:19], off
	v_or_b32_e32 v26, 0x100, v22
	v_mov_b32_e32 v27, v23
	v_lshl_add_u64 v[26:27], s[40:41], 0, v[26:27]
	v_mul_f32_e32 v9, v9, v9
	v_mul_f32_e32 v11, v11, v11
	v_fmac_f32_e32 v9, v8, v8
	v_fmac_f32_e32 v11, v10, v10
	v_add_f32_e32 v8, v9, v11
	v_add_f32_e32 v8, v12, v8
	v_or_b32_e32 v22, 0x108, v22
	v_lshl_add_u64 v[22:23], s[40:41], 0, v[22:23]
	v_pk_add_f32 v[6:7], v[6:7], v[226:227]
	v_pk_add_f32 v[4:5], v[4:5], v[224:225]
	v_cvt_pk_bf16_f32 v19, v6, v7
	v_cvt_pk_bf16_f32 v18, v4, v5
	global_store_dwordx4 v[24:25], v[4:7], off offset:512
	global_store_dwordx2 v[26:27], v[18:19], off
	v_mul_f32_e32 v5, v5, v5
	v_mul_f32_e32 v7, v7, v7
	v_fmac_f32_e32 v5, v4, v4
	v_fmac_f32_e32 v7, v6, v6
	v_add_f32_e32 v4, v5, v7
	v_add_f32_e32 v6, v8, v4
	v_pk_add_f32 v[2:3], v[2:3], v[236:237]
	v_pk_add_f32 v[0:1], v[0:1], v[234:235]
	global_store_dwordx4 v[24:25], v[0:3], off offset:528
	v_cvt_pk_bf16_f32 v4, v0, v1
	v_cvt_pk_bf16_f32 v5, v2, v3
	v_mul_f32_e32 v1, v1, v1
	v_mul_f32_e32 v3, v3, v3
	v_fmac_f32_e32 v1, v0, v0
	v_fmac_f32_e32 v3, v2, v2
	v_add_f32_e32 v0, v1, v3
	v_add_f32_e32 v0, v6, v0
	v_mov_b32_e32 v1, v0
	s_nop 1
	v_permlane16_swap_b32 v0, v1
	global_store_dwordx2 v[22:23], v[4:5], off
	v_add_f32_e32 v0, v0, v1
	v_mov_b32_e32 v1, v0
	s_nop 1
	v_permlane32_swap_b32 v0, v1
	s_and_saveexec_b64 s[12:13], s[2:3]
	s_cbranch_execz .LBB0_1621
	v_lshl_add_u64 v[2:3], v[16:17], 2, s[6:7]
	v_add_f32_e32 v0, v0, v1
	global_atomic_add_f32 v[2:3], v0, off

; __device__ __forceinline__ unsigned pk2(float lo, float hi) { f32x2_t v = {lo, hi}; bf16x2_t b = __builtin_convertvector(v, bf16x2_t); return __builtin_bit_cast(unsigned, b); }
;     __device__ __forceinline__ void operator()(const f32x4 (&acc)[2][2][4][2], const Unit& u, int wr, int wc, int fr, int fq) const {
;         const int row0 = u.pm * BM + wr * 64 + fr; constexpr int ldc = 2048; constexpr float alpha = 0.5f * ALPHA2;
;         bf16_t* const xb = (bf16_t*)(ws + XBOFF); __attribute__((address_space(1))) float* const ss = (__attribute__((address_space(1))) float*)(ws + SSOFF);
; #pragma unroll
;         for (int ai = 0; ai < 2; ++ai)
; #pragma unroll
;             for (int m = 0; m < 4; ++m) {
;                 const int row = row0 + ai * HALF + m * 16; float sq = 0.f;
; #pragma unroll
;                 for (int bj = 0; bj < 2; ++bj)
; #pragma unroll
;                     for (int n = 0; n < 2; ++n) {
;                         const size_t idx = (size_t)row * ldc + u.pn * BM + bj * HALF + wc * 32 + 8 * fq + 4 * n;
;                         const f32x4 b = *(const f32x4*)(base + idx);
;                         const f32x4 v = b + acc[ai][bj][m][n] * alpha;
;                         *(f32x4*)(out + idx) = v;
;                         if (NORM) { u32x2 w; w.x = pk2(v[0], v[1]); w.y = pk2(v[2], v[3]); *(u32x2*)(xb + idx) = w; sq += (v[0] * v[0] + v[1] * v[1]) + (v[2] * v[2] + v[3] * v[3]); }
.LBB0_1775:
	v_lshl_add_u32 v148, s14, 8, v137
	s_lshl_b32 s14, s49, 8
	s_ashr_i32 s24, s14, 31
	v_ashrrev_i32_e32 v149, 31, v148
	v_mov_b32_e32 v147, s24
	v_or_b32_e32 v146, s14, v136
	v_lshlrev_b64 v[150:151], 13, v[148:149]
	v_lshl_add_u64 v[156:157], s[30:31], 0, v[150:151]
	v_lshlrev_b64 v[150:151], 2, v[146:147]
	v_lshl_add_u64 v[146:147], v[156:157], 0, v[150:151]
	v_mov_b32_e32 v232, v146
	v_mov_b32_e32 v233, v147
	v_mov_b32_e32 v231, 0
	v_mov_b32_e32 v230, 0x0
	v_lshl_add_u64 v[228:229], v[232:233], 0, v[230:231]
	global_load_dwordx4 v[164:167], v[228:229], off
	global_load_dwordx4 v[168:171], v[228:229], off offset:16
	global_load_dwordx4 v[172:175], v[228:229], off offset:512
	global_load_dwordx4 v[176:179], v[228:229], off offset:528
	v_mov_b32_e32 v230, 0x20000
	v_lshl_add_u64 v[228:229], v[232:233], 0, v[230:231]
	global_load_dwordx4 v[180:183], v[228:229], off
	global_load_dwordx4 v[188:191], v[228:229], off offset:16
	global_load_dwordx4 v[192:195], v[228:229], off offset:512
	global_load_dwordx4 v[196:199], v[228:229], off offset:528
	v_mov_b32_e32 v230, 0x40000
	v_lshl_add_u64 v[228:229], v[232:233], 0, v[230:231]
	global_load_dwordx4 v[200:203], v[228:229], off
	global_load_dwordx4 v[204:207], v[228:229], off offset:16
	global_load_dwordx4 v[208:211], v[228:229], off offset:512
	global_load_dwordx4 v[212:215], v[228:229], off offset:528
	v_mov_b32_e32 v230, 0x60000
	v_lshl_add_u64 v[228:229], v[232:233], 0, v[230:231]
	global_load_dwordx4 v[216:219], v[228:229], off
	global_load_dwordx4 v[220:223], v[228:229], off offset:16
	global_load_dwordx4 v[224:227], v[228:229], off offset:512
	global_load_dwordx4 v[234:237], v[228:229], off offset:528
	s_mov_b64 s[24:25], -1
	s_waitcnt vmcnt(12)
	v_pk_fma_f32 v[122:123], v[122:123], 0.5, v[170:171] op_sel_hi:[1,0,1]
	v_pk_fma_f32 v[126:127], v[126:127], 0.5, v[166:167] op_sel_hi:[1,0,1]
	v_pk_fma_f32 v[124:125], v[124:125], 0.5, v[164:165] op_sel_hi:[1,0,1]
	v_pk_fma_f32 v[120:121], v[120:121], 0.5, v[168:169] op_sel_hi:[1,0,1]
	global_store_dwordx4 v[146:147], v[124:127], off
	global_store_dwordx4 v[146:147], v[120:123], off offset:16
	s_nop 0
	v_pk_fma_f32 v[114:115], v[114:115], 0.5, v[178:179] op_sel_hi:[1,0,1]
	v_pk_fma_f32 v[112:113], v[112:113], 0.5, v[176:177] op_sel_hi:[1,0,1]
	global_store_dwordx4 v[146:147], v[112:115], off offset:528
	v_pk_fma_f32 v[118:119], v[118:119], 0.5, v[174:175] op_sel_hi:[1,0,1]
	v_pk_fma_f32 v[116:117], v[116:117], 0.5, v[172:173] op_sel_hi:[1,0,1]
	v_mov_b32_e32 v230, 0x100000
	v_lshl_add_u64 v[228:229], v[232:233], 0, v[230:231]
	global_load_dwordx4 v[164:167], v[228:229], off
	global_load_dwordx4 v[168:171], v[228:229], off offset:16
	global_load_dwordx4 v[172:175], v[228:229], off offset:512
	global_load_dwordx4 v[176:179], v[228:229], off offset:528
	v_or_b32_e32 v112, 16, v148
	v_ashrrev_i32_e32 v113, 31, v112
	v_lshlrev_b64 v[112:113], 13, v[112:113]
	v_lshl_add_u64 v[112:113], s[30:31], 0, v[112:113]
	global_store_dwordx4 v[146:147], v[116:119], off offset:512
	v_lshl_add_u64 v[120:121], v[112:113], 0, v[150:151]
	s_waitcnt vmcnt(16)
	v_pk_fma_f32 v[106:107], v[106:107], 0.5, v[190:191] op_sel_hi:[1,0,1]
	v_pk_fma_f32 v[110:111], v[110:111], 0.5, v[182:183] op_sel_hi:[1,0,1]
	v_pk_fma_f32 v[108:109], v[108:109], 0.5, v[180:181] op_sel_hi:[1,0,1]
	v_pk_fma_f32 v[104:105], v[104:105], 0.5, v[188:189] op_sel_hi:[1,0,1]
	global_store_dwordx4 v[120:121], v[108:111], off
	global_store_dwordx4 v[120:121], v[104:107], off offset:16
	s_nop 0
	v_pk_fma_f32 v[98:99], v[98:99], 0.5, v[198:199] op_sel_hi:[1,0,1]
	v_pk_fma_f32 v[96:97], v[96:97], 0.5, v[196:197] op_sel_hi:[1,0,1]
	global_store_dwordx4 v[120:121], v[96:99], off offset:528
	v_pk_fma_f32 v[102:103], v[102:103], 0.5, v[194:195] op_sel_hi:[1,0,1]
	v_pk_fma_f32 v[100:101], v[100:101], 0.5, v[192:193] op_sel_hi:[1,0,1]
	v_mov_b32_e32 v230, 0x120000
	v_lshl_add_u64 v[228:229], v[232:233], 0, v[230:231]
	global_load_dwordx4 v[180:183], v[228:229], off
	global_load_dwordx4 v[188:191], v[228:229], off offset:16
	global_load_dwordx4 v[192:195], v[228:229], off offset:512
	global_load_dwordx4 v[196:199], v[228:229], off offset:528
	v_or_b32_e32 v96, 32, v148
	v_ashrrev_i32_e32 v97, 31, v96
	v_lshlrev_b64 v[96:97], 13, v[96:97]
	v_lshl_add_u64 v[96:97], s[30:31], 0, v[96:97]
	global_store_dwordx4 v[120:121], v[100:103], off offset:512
	v_lshl_add_u64 v[104:105], v[96:97], 0, v[150:151]
	s_waitcnt vmcnt(20)
	v_pk_fma_f32 v[90:91], v[90:91], 0.5, v[206:207] op_sel_hi:[1,0,1]
	v_pk_fma_f32 v[94:95], v[94:95], 0.5, v[202:203] op_sel_hi:[1,0,1]
	v_pk_fma_f32 v[92:93], v[92:93], 0.5, v[200:201] op_sel_hi:[1,0,1]
	v_pk_fma_f32 v[88:89], v[88:89], 0.5, v[204:205] op_sel_hi:[1,0,1]
	global_store_dwordx4 v[104:105], v[92:95], off
	global_store_dwordx4 v[104:105], v[88:91], off offset:16
	s_nop 0
	v_pk_fma_f32 v[82:83], v[82:83], 0.5, v[214:215] op_sel_hi:[1,0,1]
	v_pk_fma_f32 v[80:81], v[80:81], 0.5, v[212:213] op_sel_hi:[1,0,1]
	global_store_dwordx4 v[104:105], v[80:83], off offset:528
	v_pk_fma_f32 v[86:87], v[86:87], 0.5, v[210:211] op_sel_hi:[1,0,1]
	v_pk_fma_f32 v[84:85], v[84:85], 0.5, v[208:209] op_sel_hi:[1,0,1]
	v_mov_b32_e32 v230, 0x140000
	v_lshl_add_u64 v[228:229], v[232:233], 0, v[230:231]
	global_load_dwordx4 v[200:203], v[228:229], off
	global_load_dwordx4 v[204:207], v[228:229], off offset:16
	global_load_dwordx4 v[208:211], v[228:229], off offset:512
	global_load_dwordx4 v[212:215], v[228:229], off offset:528
	v_or_b32_e32 v80, 48, v148
	v_ashrrev_i32_e32 v81, 31, v80
	v_lshlrev_b64 v[80:81], 13, v[80:81]
	v_lshl_add_u64 v[80:81], s[30:31], 0, v[80:81]
	global_store_dwordx4 v[104:105], v[84:87], off offset:512
	v_lshl_add_u64 v[88:89], v[80:81], 0, v[150:151]
	s_waitcnt vmcnt(24)
; __device__ __forceinline__ unsigned pk2(float lo, float hi) { f32x2_t v = {lo, hi}; bf16x2_t b = __builtin_convertvector(v, bf16x2_t); return __builtin_bit_cast(unsigned, b); }
; #define PG8_BAR __builtin_amdgcn_s_barrier()
;     __device__ __forceinline__ void operator()(const f32x4 (&acc)[2][2][4][2], const Unit& u, int wr, int wc, int fr, int fq) const {
;     ...
;                 const int row = row0 + ai * HALF + m * 16; float sq = 0.f;
; #pragma unroll
;                 for (int bj = 0; bj < 2; ++bj)
; #pragma unroll
;                     for (int n = 0; n < 2; ++n) {
;                         const size_t idx = (size_t)row * ldc + u.pn * BM + bj * HALF + wc * 32 + 8 * fq + 4 * n;
;                         const f32x4 b = *(const f32x4*)(base + idx);
;                         const f32x4 v = b + acc[ai][bj][m][n] * alpha;
;                         *(f32x4*)(out + idx) = v;
;                         if (NORM) { u32x2 w; w.x = pk2(v[0], v[1]); w.y = pk2(v[2], v[3]); *(u32x2*)(xb + idx) = w; sq += (v[0] * v[0] + v[1] * v[1]) + (v[2] * v[2] + v[3] * v[3]); }
; template <class Epi, bool ALIGN_EPI = PG8_ALIGN>
; __device__ __forceinline__ void gemm_phase(LAS unsigned char* lds, const Gemm g, const StaticOrder S, const Epi E) {
;     ...
;         if (!has_next) break;
; #pragma unroll
;         for (int a = 0; a < 2; ++a)
; #pragma unroll
;             for (int b = 0; b < 2; ++b)
; #pragma unroll
;                 for (int m = 0; m < 4; ++m)
; #pragma unroll
;                     for (int n = 0; n < 2; ++n) acc[a][b][m][n] = (f32x4){0.f, 0.f, 0.f, 0.f};
;         cur = nxt; cA = nA; cB = nB; ++ui;
;         if (ALIGN_EPI) { if (wr == 1) PG8_BAR; }
	v_pk_fma_f32 v[74:75], v[74:75], 0.5, v[222:223] op_sel_hi:[1,0,1]
	v_pk_fma_f32 v[78:79], v[78:79], 0.5, v[218:219] op_sel_hi:[1,0,1]
	v_pk_fma_f32 v[76:77], v[76:77], 0.5, v[216:217] op_sel_hi:[1,0,1]
	v_pk_fma_f32 v[72:73], v[72:73], 0.5, v[220:221] op_sel_hi:[1,0,1]
	global_store_dwordx4 v[88:89], v[76:79], off
	global_store_dwordx4 v[88:89], v[72:75], off offset:16
	s_nop 0
	v_pk_fma_f32 v[66:67], v[66:67], 0.5, v[236:237] op_sel_hi:[1,0,1]
	v_pk_fma_f32 v[70:71], v[70:71], 0.5, v[226:227] op_sel_hi:[1,0,1]
	v_pk_fma_f32 v[68:69], v[68:69], 0.5, v[224:225] op_sel_hi:[1,0,1]
	v_pk_fma_f32 v[64:65], v[64:65], 0.5, v[234:235] op_sel_hi:[1,0,1]
	v_mov_b32_e32 v230, 0x160000
	v_lshl_add_u64 v[228:229], v[232:233], 0, v[230:231]
	global_load_dwordx4 v[216:219], v[228:229], off
	global_load_dwordx4 v[220:223], v[228:229], off offset:16
	global_load_dwordx4 v[224:227], v[228:229], off offset:512
	global_load_dwordx4 v[234:237], v[228:229], off offset:528
	v_add_co_u32_e32 v74, vcc, s43, v146
	global_store_dwordx4 v[88:89], v[68:71], off offset:512
	global_store_dwordx4 v[88:89], v[64:67], off offset:528
	v_addc_co_u32_e32 v75, vcc, 0, v147, vcc
	v_lshl_add_u64 v[72:73], v[146:147], 0, s[12:13]
	s_waitcnt vmcnt(25)
	v_pk_fma_f32 v[62:63], v[62:63], 0.5, v[166:167] op_sel_hi:[1,0,1]
	v_pk_fma_f32 v[60:61], v[60:61], 0.5, v[164:165] op_sel_hi:[1,0,1]
	v_pk_fma_f32 v[58:59], v[58:59], 0.5, v[170:171] op_sel_hi:[1,0,1]
	v_pk_fma_f32 v[56:57], v[56:57], 0.5, v[168:169] op_sel_hi:[1,0,1]
	global_store_dwordx4 v[74:75], v[60:63], off
	global_store_dwordx4 v[72:73], v[56:59], off offset:16
	s_nop 0
	v_pk_fma_f32 v[50:51], v[50:51], 0.5, v[178:179] op_sel_hi:[1,0,1]
	v_pk_fma_f32 v[54:55], v[54:55], 0.5, v[174:175] op_sel_hi:[1,0,1]
	v_pk_fma_f32 v[52:53], v[52:53], 0.5, v[172:173] op_sel_hi:[1,0,1]
	v_pk_fma_f32 v[48:49], v[48:49], 0.5, v[176:177] op_sel_hi:[1,0,1]
	v_add_co_u32_e32 v58, vcc, s44, v146
	global_store_dwordx4 v[72:73], v[52:55], off offset:512
	global_store_dwordx4 v[72:73], v[48:51], off offset:528
	v_addc_co_u32_e32 v59, vcc, 0, v147, vcc
	v_lshl_add_u64 v[56:57], v[146:147], 0, s[18:19]
	s_waitcnt vmcnt(21)
	v_pk_fma_f32 v[46:47], v[46:47], 0.5, v[182:183] op_sel_hi:[1,0,1]
	v_pk_fma_f32 v[44:45], v[44:45], 0.5, v[180:181] op_sel_hi:[1,0,1]
	v_pk_fma_f32 v[42:43], v[42:43], 0.5, v[190:191] op_sel_hi:[1,0,1]
	v_pk_fma_f32 v[40:41], v[40:41], 0.5, v[188:189] op_sel_hi:[1,0,1]
	global_store_dwordx4 v[58:59], v[44:47], off
	global_store_dwordx4 v[56:57], v[40:43], off offset:16
	s_nop 0
	v_pk_fma_f32 v[34:35], v[34:35], 0.5, v[198:199] op_sel_hi:[1,0,1]
	v_pk_fma_f32 v[38:39], v[38:39], 0.5, v[194:195] op_sel_hi:[1,0,1]
	v_pk_fma_f32 v[36:37], v[36:37], 0.5, v[192:193] op_sel_hi:[1,0,1]
	v_pk_fma_f32 v[32:33], v[32:33], 0.5, v[196:197] op_sel_hi:[1,0,1]
	v_add_co_u32_e32 v42, vcc, s45, v146
	global_store_dwordx4 v[56:57], v[36:39], off offset:512
	global_store_dwordx4 v[56:57], v[32:35], off offset:528
	v_addc_co_u32_e32 v43, vcc, 0, v147, vcc
	v_lshl_add_u64 v[40:41], v[146:147], 0, s[20:21]
	s_waitcnt vmcnt(17)
	v_pk_fma_f32 v[30:31], v[30:31], 0.5, v[202:203] op_sel_hi:[1,0,1]
	v_pk_fma_f32 v[28:29], v[28:29], 0.5, v[200:201] op_sel_hi:[1,0,1]
	v_pk_fma_f32 v[26:27], v[26:27], 0.5, v[206:207] op_sel_hi:[1,0,1]
	v_pk_fma_f32 v[24:25], v[24:25], 0.5, v[204:205] op_sel_hi:[1,0,1]
	global_store_dwordx4 v[42:43], v[28:31], off
	global_store_dwordx4 v[40:41], v[24:27], off offset:16
	s_nop 0
	v_pk_fma_f32 v[18:19], v[18:19], 0.5, v[214:215] op_sel_hi:[1,0,1]
	v_pk_fma_f32 v[22:23], v[22:23], 0.5, v[210:211] op_sel_hi:[1,0,1]
	v_pk_fma_f32 v[20:21], v[20:21], 0.5, v[208:209] op_sel_hi:[1,0,1]
	v_pk_fma_f32 v[16:17], v[16:17], 0.5, v[212:213] op_sel_hi:[1,0,1]
	v_add_co_u32_e32 v26, vcc, s46, v146
	global_store_dwordx4 v[40:41], v[20:23], off offset:512
	global_store_dwordx4 v[40:41], v[16:19], off offset:528
	v_addc_co_u32_e32 v27, vcc, 0, v147, vcc
	s_nop 0
	v_lshl_add_u64 v[16:17], v[146:147], 0, s[4:5]
	s_and_b64 vcc, exec, s[0:1]
	s_waitcnt vmcnt(14)
	v_pk_fma_f32 v[14:15], v[14:15], 0.5, v[218:219] op_sel_hi:[1,0,1]
	v_pk_fma_f32 v[12:13], v[12:13], 0.5, v[216:217] op_sel_hi:[1,0,1]
	v_pk_fma_f32 v[10:11], v[10:11], 0.5, v[222:223] op_sel_hi:[1,0,1]
	v_pk_fma_f32 v[8:9], v[8:9], 0.5, v[220:221] op_sel_hi:[1,0,1]
	global_store_dwordx4 v[26:27], v[12:15], off
	global_store_dwordx4 v[16:17], v[8:11], off offset:16
	s_nop 0
	v_pk_fma_f32 v[2:3], v[2:3], 0.5, v[236:237] op_sel_hi:[1,0,1]
	v_pk_fma_f32 v[6:7], v[6:7], 0.5, v[226:227] op_sel_hi:[1,0,1]
	v_pk_fma_f32 v[4:5], v[4:5], 0.5, v[224:225] op_sel_hi:[1,0,1]
	v_pk_fma_f32 v[0:1], v[0:1], 0.5, v[234:235] op_sel_hi:[1,0,1]
	global_store_dwordx4 v[16:17], v[4:7], off offset:512
	global_store_dwordx4 v[16:17], v[0:3], off offset:528
	s_cbranch_vccnz .LBB0_1760
	s_andn2_b64 vcc, exec, s[6:7]
	s_cbranch_vccnz .LBB0_1759
	s_barrier
	s_branch .LBB0_1759
